# cache policy by data age: gate-epilogue h2 loads (written one phase earlier by the same XCD) back to default policy; nt kept on long-ago-written / input streams
# speedup vs baseline: 1.0145x; 1.0145x over previous
; __device__ __forceinline__ f32x4 acc_i2f(const f32x4 a) { return __builtin_convertvector(__builtin_bit_cast(i32x4, a), f32x4); }
;     __device__ __forceinline__ void operator()(const f32x4 (&acc)[2][2][4][2], const pg8::Unit& u, int wr, int wc, int fr, int fq) const {
;         const int row0 = u.pm * 256 + wr * 64 + fr, col0 = u.pn * 256 + wc * 32 + 8 * fq;
;         f32x4 bv[2][2], sb[2][2];
; #pragma unroll
;         for (int bj = 0; bj < 2; ++bj) { bv[bj][0] = *(const f32x4*)(bg + col0 + bj * 128); bv[bj][1] = *(const f32x4*)(bg + col0 + bj * 128 + 4);
;             sb[bj][0] = *(const f32x4*)(cmax + col0 + bj * 128) * (1.f / 127.f); sb[bj][1] = *(const f32x4*)(cmax + col0 + bj * 128 + 4) * (1.f / 127.f); }
; #pragma unroll
;         for (int ai = 0; ai < 2; ++ai)
; #pragma unroll
;             for (int mp = 0; mp < 2; ++mp) {
;                 u32x4 hr[2][2], pr[2][2]; float q1v[2];
; #pragma unroll
;                 for (int mm = 0; mm < 2; ++mm) { const int row = row0 + ai * 128 + (2 * mp + mm) * 16; q1v[mm] = rss1[row];
; #pragma unroll
;                     for (int bj = 0; bj < 2; ++bj) { const size_t off = (size_t)row * DM + col0 + bj * 128; hr[mm][bj] = *(const u32x4*)(HB + off); pr[mm][bj] = *(const u32x4*)(PP + off); } }
; #pragma unroll
;                 for (int mm = 0; mm < 2; ++mm) { const int m = 2 * mp + mm, row = row0 + ai * 128 + m * 16; f32x4 ssv = {0.f, 0.f, 0.f, 0.f}; const float sa = (QCLIP / 127.f) * sqrtf(q1v[mm] * (1.f / DM) + EPS);
; #pragma unroll
;                     for (int bj = 0; bj < 2; ++bj) { const size_t off = (size_t)row * DM + col0 + bj * 128;
;                         f32x4 p0, p1, x0, x1; unpack8v(pr[mm][bj], p0, p1); unpack8v(hr[mm][bj], x0, x1);
;                         const f32x4 g0 = acc_i2f(acc[ai][bj][m][0]) * (sb[bj][0] * sa) + bv[bj][0], g1 = acc_i2f(acc[ai][bj][m][1]) * (sb[bj][1] * sa) + bv[bj][1];
;                         const f32x4 h0 = x0 + p0 * sigm4(g0), h1 = x1 + p1 * sigm4(g1);
;                         *(f32x4*)(H + off) = h0; *(f32x4*)(H + off + 4) = h1;
;                         ssv = ssv + h0 * h0; ssv = ssv + h1 * h1; }
;                     float ss = (ssv[0] + ssv[1]) + (ssv[2] + ssv[3]);
;                     ss += __shfl_xor(ss, 16); ss += __shfl_xor(ss, 32);
;                     if (fq == 0) unsafeAtomicAdd(rss3 + row, ss); }
.LBB0_1460:
	s_cmpk_lg_i32 s74, 0x100
	s_cbranch_scc1 .Lp8_orig_epi
	s_mov_b32 s98, s10
	s_mov_b32 s99, s46
	v_lshlrev_b32_e32 v54, 2, v1
	v_lshlrev_b32_e32 v55, 2, v199
	v_lshlrev_b32_e32 v56, 13, v1
	v_lshlrev_b32_e32 v57, 14, v1
	v_lshl_add_u32 v56, v199, 1, v56
	v_lshl_add_u32 v57, v199, 2, v57
	v_xor_b32_e32 v58, 16, v203
	v_xor_b32_e32 v59, 32, v203
	v_lshlrev_b32_e32 v58, 2, v58
	v_lshlrev_b32_e32 v59, 2, v59
	s_lshl_b32 s48, s99, 10
	s_add_u32 s50, s14, s48
	s_addc_u32 s51, s15, 0
	s_add_u32 s52, s18, s48
	s_addc_u32 s53, s19, 0
	s_lshl_b32 s49, s98, 10
	s_add_u32 s68, s28, s49
	s_addc_u32 s69, s29, 0
	s_add_u32 s70, s26, s49
	s_addc_u32 s71, s27, 0
	s_lshl_b32 s72, s98, 21
	s_lshl_b32 s73, s99, 9
	s_add_u32 s72, s72, s73
	s_add_u32 s86, s22, s72
	s_addc_u32 s87, s23, 0
	s_add_u32 s88, s24, s72
	s_addc_u32 s89, s25, 0
	s_lshl_b32 s72, s98, 22
	s_add_u32 s72, s72, s48
	s_add_u32 s84, s12, s72
	s_addc_u32 s85, s13, 0
	global_load_dwordx4 v[222:225], v55, s[50:51]
	global_load_dwordx4 v[226:229], v55, s[50:51] offset:16
	global_load_dwordx4 v[230:233], v55, s[50:51] offset:512
	global_load_dwordx4 v[234:237], v55, s[50:51] offset:528
	global_load_dwordx4 v[206:209], v55, s[52:53]
	global_load_dwordx4 v[210:213], v55, s[52:53] offset:16
	global_load_dwordx4 v[214:217], v55, s[52:53] offset:512
	global_load_dwordx4 v[218:221], v55, s[52:53] offset:528
	global_load_dword v66, v54, s[68:69]
	global_load_dwordx4 v[238:241], v56, s[86:87]
	global_load_dwordx4 v[242:245], v56, s[86:87] offset:256
	global_load_dwordx4 v[246:249], v56, s[88:89] nt
	global_load_dwordx4 v[250:253], v56, s[88:89] offset:256 nt
	s_add_u32 s86, s86, 0x20000
	s_addc_u32 s87, s87, 0
	s_add_u32 s88, s88, 0x20000
	s_addc_u32 s89, s89, 0
	global_load_dword v67, v54, s[68:69] offset:64
	global_load_dwordx4 v[170:173], v56, s[86:87]
	global_load_dwordx4 v[174:177], v56, s[86:87] offset:256
	global_load_dwordx4 v[178:181], v56, s[88:89] nt
	global_load_dwordx4 v[182:185], v56, s[88:89] offset:256 nt
	s_add_u32 s86, s86, 0x20000
	s_addc_u32 s87, s87, 0
	s_add_u32 s88, s88, 0x20000
	s_addc_u32 s89, s89, 0
	s_waitcnt vmcnt(5)
	v_pk_mul_f32 v[222:223], v[222:223], s[36:37] op_sel_hi:[1,0]
	v_pk_mul_f32 v[224:225], v[224:225], s[36:37] op_sel_hi:[1,0]
	v_pk_mul_f32 v[226:227], v[226:227], s[36:37] op_sel_hi:[1,0]
	v_pk_mul_f32 v[228:229], v[228:229], s[36:37] op_sel_hi:[1,0]
	v_pk_mul_f32 v[230:231], v[230:231], s[36:37] op_sel_hi:[1,0]
	v_pk_mul_f32 v[232:233], v[232:233], s[36:37] op_sel_hi:[1,0]
	v_pk_mul_f32 v[234:235], v[234:235], s[36:37] op_sel_hi:[1,0]
	v_pk_mul_f32 v[236:237], v[236:237], s[36:37] op_sel_hi:[1,0]
	v_fmamk_f32 v186, v66, 0x39800000, v204
	v_mul_f32_e32 v187, 0x4f800000, v186
	v_cmp_gt_f32_e32 vcc, s67, v186
	s_nop 1
	v_cndmask_b32_e32 v186, v186, v187, vcc
	v_sqrt_f32_e32 v190, v186
	s_nop 0
	v_add_u32_e32 v191, -1, v190
	v_add_u32_e32 v192, 1, v190
	v_fma_f32 v193, -v191, v190, v186
	v_fma_f32 v187, -v192, v190, v186
	v_cmp_ge_f32_e64 s[10:11], 0, v193
	s_nop 1
	v_cndmask_b32_e64 v190, v190, v191, s[10:11]
	v_cmp_lt_f32_e64 s[10:11], 0, v187
	s_nop 1
	v_cndmask_b32_e64 v190, v190, v192, s[10:11]
	v_mul_f32_e32 v191, 0x37800000, v190
	v_cndmask_b32_e32 v190, v190, v191, vcc
	v_cmp_class_f32_e32 vcc, v186, v205
	s_nop 1
	v_cndmask_b32_e32 v186, v190, v186, vcc
	v_mul_f32_e32 v188, 0x3d112245, v186
	v_cvt_f32_i32_e32 v50, v50
	v_cvt_f32_i32_e32 v51, v51
	v_cvt_f32_i32_e32 v52, v52
	v_cvt_f32_i32_e32 v53, v53
	v_pk_mul_f32 v[142:143], v[222:223], v[188:189] op_sel_hi:[1,0]
	v_pk_mul_f32 v[144:145], v[224:225], v[188:189] op_sel_hi:[1,0]
	v_pk_fma_f32 v[154:155], v[142:143], v[50:51], v[206:207]
	v_pk_fma_f32 v[156:157], v[144:145], v[52:53], v[208:209]
	v_mul_f32_e32 v154, 0xbfb8aa3b, v154
	v_mul_f32_e32 v155, 0xbfb8aa3b, v155
	v_mul_f32_e32 v156, 0xbfb8aa3b, v156
	v_mul_f32_e32 v157, 0xbfb8aa3b, v157
	v_exp_f32_e32 v154, v154
	v_exp_f32_e32 v155, v155
	v_exp_f32_e32 v156, v156
	v_exp_f32_e32 v157, v157
	v_lshlrev_b32_e32 v146, 16, v238
	v_and_b32_e32 v147, 0xffff0000, v238
	v_lshlrev_b32_e32 v148, 16, v239
	v_and_b32_e32 v149, 0xffff0000, v239
	v_add_f32_e32 v154, 1.0, v154
	v_add_f32_e32 v155, 1.0, v155
	v_add_f32_e32 v156, 1.0, v156
	v_add_f32_e32 v157, 1.0, v157
	v_rcp_f32_e32 v154, v154
	v_rcp_f32_e32 v155, v155
	v_rcp_f32_e32 v156, v156
	v_rcp_f32_e32 v157, v157
	v_lshlrev_b32_e32 v150, 16, v246
	v_and_b32_e32 v151, 0xffff0000, v246
	v_lshlrev_b32_e32 v152, 16, v247
	v_and_b32_e32 v153, 0xffff0000, v247
	v_pk_fma_f32 v[50:51], v[154:155], v[150:151], v[146:147]
	v_pk_fma_f32 v[52:53], v[156:157], v[152:153], v[148:149]
	v_pk_mul_f32 v[194:195], v[50:51], v[50:51]
	v_pk_mul_f32 v[196:197], v[52:53], v[52:53]
	v_cvt_f32_i32_e32 v138, v138
	v_cvt_f32_i32_e32 v139, v139
	v_cvt_f32_i32_e32 v140, v140
	v_cvt_f32_i32_e32 v141, v141
	v_pk_mul_f32 v[142:143], v[226:227], v[188:189] op_sel_hi:[1,0]
	v_pk_mul_f32 v[144:145], v[228:229], v[188:189] op_sel_hi:[1,0]
	v_pk_fma_f32 v[154:155], v[142:143], v[138:139], v[210:211]
	v_pk_fma_f32 v[156:157], v[144:145], v[140:141], v[212:213]
	v_mul_f32_e32 v154, 0xbfb8aa3b, v154
	v_mul_f32_e32 v155, 0xbfb8aa3b, v155
	v_mul_f32_e32 v156, 0xbfb8aa3b, v156
	v_mul_f32_e32 v157, 0xbfb8aa3b, v157
	v_exp_f32_e32 v154, v154
	v_exp_f32_e32 v155, v155
	v_exp_f32_e32 v156, v156
	v_exp_f32_e32 v157, v157
	v_lshlrev_b32_e32 v146, 16, v240
	v_and_b32_e32 v147, 0xffff0000, v240
	v_lshlrev_b32_e32 v148, 16, v241
	v_and_b32_e32 v149, 0xffff0000, v241
	v_add_f32_e32 v154, 1.0, v154
	v_add_f32_e32 v155, 1.0, v155
	v_add_f32_e32 v156, 1.0, v156
	v_add_f32_e32 v157, 1.0, v157
	v_rcp_f32_e32 v154, v154
	v_rcp_f32_e32 v155, v155
; __device__ __forceinline__ f32x4 acc_i2f(const f32x4 a) { return __builtin_convertvector(__builtin_bit_cast(i32x4, a), f32x4); }
;     __device__ __forceinline__ void operator()(const f32x4 (&acc)[2][2][4][2], const pg8::Unit& u, int wr, int wc, int fr, int fq) const {
;     ...
;                 for (int mm = 0; mm < 2; ++mm) { const int m = 2 * mp + mm, row = row0 + ai * 128 + m * 16; f32x4 ssv = {0.f, 0.f, 0.f, 0.f}; const float sa = (QCLIP / 127.f) * sqrtf(q1v[mm] * (1.f / DM) + EPS);
; #pragma unroll
;                     for (int bj = 0; bj < 2; ++bj) { const size_t off = (size_t)row * DM + col0 + bj * 128;
;                         f32x4 p0, p1, x0, x1; unpack8v(pr[mm][bj], p0, p1); unpack8v(hr[mm][bj], x0, x1);
;                         const f32x4 g0 = acc_i2f(acc[ai][bj][m][0]) * (sb[bj][0] * sa) + bv[bj][0], g1 = acc_i2f(acc[ai][bj][m][1]) * (sb[bj][1] * sa) + bv[bj][1];
;                         const f32x4 h0 = x0 + p0 * sigm4(g0), h1 = x1 + p1 * sigm4(g1);
;                         *(f32x4*)(H + off) = h0; *(f32x4*)(H + off + 4) = h1;
;                         ssv = ssv + h0 * h0; ssv = ssv + h1 * h1; }
;                     float ss = (ssv[0] + ssv[1]) + (ssv[2] + ssv[3]);
;                     ss += __shfl_xor(ss, 16); ss += __shfl_xor(ss, 32);
;                     if (fq == 0) unsafeAtomicAdd(rss3 + row, ss); }
	v_rcp_f32_e32 v156, v156
	v_rcp_f32_e32 v157, v157
	v_lshlrev_b32_e32 v150, 16, v248
	v_and_b32_e32 v151, 0xffff0000, v248
	v_lshlrev_b32_e32 v152, 16, v249
	v_and_b32_e32 v153, 0xffff0000, v249
	v_pk_fma_f32 v[138:139], v[154:155], v[150:151], v[146:147]
	v_pk_fma_f32 v[140:141], v[156:157], v[152:153], v[148:149]
	v_pk_fma_f32 v[194:195], v[138:139], v[138:139], v[194:195]
	v_pk_fma_f32 v[196:197], v[140:141], v[140:141], v[196:197]
	v_cvt_f32_i32_e32 v134, v134
	v_cvt_f32_i32_e32 v135, v135
	v_cvt_f32_i32_e32 v136, v136
	v_cvt_f32_i32_e32 v137, v137
	v_pk_mul_f32 v[142:143], v[230:231], v[188:189] op_sel_hi:[1,0]
	v_pk_mul_f32 v[144:145], v[232:233], v[188:189] op_sel_hi:[1,0]
	v_pk_fma_f32 v[154:155], v[142:143], v[134:135], v[214:215]
	v_pk_fma_f32 v[156:157], v[144:145], v[136:137], v[216:217]
	v_mul_f32_e32 v154, 0xbfb8aa3b, v154
	v_mul_f32_e32 v155, 0xbfb8aa3b, v155
	v_mul_f32_e32 v156, 0xbfb8aa3b, v156
	v_mul_f32_e32 v157, 0xbfb8aa3b, v157
	v_exp_f32_e32 v154, v154
	v_exp_f32_e32 v155, v155
	v_exp_f32_e32 v156, v156
	v_exp_f32_e32 v157, v157
	v_lshlrev_b32_e32 v146, 16, v242
	v_and_b32_e32 v147, 0xffff0000, v242
	v_lshlrev_b32_e32 v148, 16, v243
	v_and_b32_e32 v149, 0xffff0000, v243
	v_add_f32_e32 v154, 1.0, v154
	v_add_f32_e32 v155, 1.0, v155
	v_add_f32_e32 v156, 1.0, v156
	v_add_f32_e32 v157, 1.0, v157
	v_rcp_f32_e32 v154, v154
	v_rcp_f32_e32 v155, v155
	v_rcp_f32_e32 v156, v156
	v_rcp_f32_e32 v157, v157
	v_lshlrev_b32_e32 v150, 16, v250
	v_and_b32_e32 v151, 0xffff0000, v250
	v_lshlrev_b32_e32 v152, 16, v251
	v_and_b32_e32 v153, 0xffff0000, v251
	v_pk_fma_f32 v[134:135], v[154:155], v[150:151], v[146:147]
	v_pk_fma_f32 v[136:137], v[156:157], v[152:153], v[148:149]
	v_pk_fma_f32 v[194:195], v[134:135], v[134:135], v[194:195]
	v_pk_fma_f32 v[196:197], v[136:137], v[136:137], v[196:197]
	v_cvt_f32_i32_e32 v130, v130
	v_cvt_f32_i32_e32 v131, v131
	v_cvt_f32_i32_e32 v132, v132
	v_cvt_f32_i32_e32 v133, v133
	v_pk_mul_f32 v[142:143], v[234:235], v[188:189] op_sel_hi:[1,0]
	v_pk_mul_f32 v[144:145], v[236:237], v[188:189] op_sel_hi:[1,0]
	v_pk_fma_f32 v[154:155], v[142:143], v[130:131], v[218:219]
	v_pk_fma_f32 v[156:157], v[144:145], v[132:133], v[220:221]
	v_mul_f32_e32 v154, 0xbfb8aa3b, v154
	v_mul_f32_e32 v155, 0xbfb8aa3b, v155
	v_mul_f32_e32 v156, 0xbfb8aa3b, v156
	v_mul_f32_e32 v157, 0xbfb8aa3b, v157
	v_exp_f32_e32 v154, v154
	v_exp_f32_e32 v155, v155
	v_exp_f32_e32 v156, v156
	v_exp_f32_e32 v157, v157
	v_lshlrev_b32_e32 v146, 16, v244
	v_and_b32_e32 v147, 0xffff0000, v244
	v_lshlrev_b32_e32 v148, 16, v245
	v_and_b32_e32 v149, 0xffff0000, v245
	v_add_f32_e32 v154, 1.0, v154
	v_add_f32_e32 v155, 1.0, v155
	v_add_f32_e32 v156, 1.0, v156
	v_add_f32_e32 v157, 1.0, v157
	v_rcp_f32_e32 v154, v154
	v_rcp_f32_e32 v155, v155
	v_rcp_f32_e32 v156, v156
	v_rcp_f32_e32 v157, v157
	v_lshlrev_b32_e32 v150, 16, v252
	v_and_b32_e32 v151, 0xffff0000, v252
	v_lshlrev_b32_e32 v152, 16, v253
	v_and_b32_e32 v153, 0xffff0000, v253
	v_pk_fma_f32 v[130:131], v[154:155], v[150:151], v[146:147]
	v_pk_fma_f32 v[132:133], v[156:157], v[152:153], v[148:149]
	v_pk_fma_f32 v[194:195], v[130:131], v[130:131], v[194:195]
	v_pk_fma_f32 v[196:197], v[132:133], v[132:133], v[196:197]
	v_add_f32_e32 v194, v194, v195
	v_add_f32_e32 v196, v196, v197
	v_add_f32_e32 v194, v194, v196
	ds_bpermute_b32 v195, v58, v194
	s_waitcnt lgkmcnt(0)
	v_add_f32_e32 v194, v194, v195
	ds_bpermute_b32 v195, v59, v194
	s_waitcnt lgkmcnt(0)
	v_add_f32_e32 v194, v194, v195
	s_and_saveexec_b64 s[32:33], s[6:7]
	global_atomic_add_f32 v54, v194, s[70:71]
	s_or_b64 exec, exec, s[32:33]
	global_load_dword v66, v54, s[68:69] offset:128
	global_load_dwordx4 v[238:241], v56, s[86:87]
	global_load_dwordx4 v[242:245], v56, s[86:87] offset:256
	global_load_dwordx4 v[246:249], v56, s[88:89] nt
	global_load_dwordx4 v[250:253], v56, s[88:89] offset:256 nt
	s_add_u32 s86, s86, 0x20000
	s_addc_u32 s87, s87, 0
	s_add_u32 s88, s88, 0x20000
	s_addc_u32 s89, s89, 0
	s_waitcnt vmcnt(6)
	v_fmamk_f32 v186, v67, 0x39800000, v204
	v_mul_f32_e32 v187, 0x4f800000, v186
	v_cmp_gt_f32_e32 vcc, s67, v186
	s_nop 1
	v_cndmask_b32_e32 v186, v186, v187, vcc
	v_sqrt_f32_e32 v190, v186
	s_nop 0
	v_add_u32_e32 v191, -1, v190
	v_add_u32_e32 v192, 1, v190
	v_fma_f32 v193, -v191, v190, v186
	v_fma_f32 v187, -v192, v190, v186
	v_cmp_ge_f32_e64 s[10:11], 0, v193
	s_nop 1
	v_cndmask_b32_e64 v190, v190, v191, s[10:11]
	v_cmp_lt_f32_e64 s[10:11], 0, v187
	s_nop 1
	v_cndmask_b32_e64 v190, v190, v192, s[10:11]
	v_mul_f32_e32 v191, 0x37800000, v190
	v_cndmask_b32_e32 v190, v190, v191, vcc
	v_cmp_class_f32_e32 vcc, v186, v205
	s_nop 1
	v_cndmask_b32_e32 v186, v190, v186, vcc
	v_mul_f32_e32 v188, 0x3d112245, v186
	v_cvt_f32_i32_e32 v126, v126
	v_cvt_f32_i32_e32 v127, v127
	v_cvt_f32_i32_e32 v128, v128
	v_cvt_f32_i32_e32 v129, v129
	v_pk_mul_f32 v[142:143], v[222:223], v[188:189] op_sel_hi:[1,0]
	v_pk_mul_f32 v[144:145], v[224:225], v[188:189] op_sel_hi:[1,0]
	v_pk_fma_f32 v[154:155], v[142:143], v[126:127], v[206:207]
	v_pk_fma_f32 v[156:157], v[144:145], v[128:129], v[208:209]
	v_mul_f32_e32 v154, 0xbfb8aa3b, v154
	v_mul_f32_e32 v155, 0xbfb8aa3b, v155
	v_mul_f32_e32 v156, 0xbfb8aa3b, v156
	v_mul_f32_e32 v157, 0xbfb8aa3b, v157
	v_exp_f32_e32 v154, v154
	v_exp_f32_e32 v155, v155
	v_exp_f32_e32 v156, v156
	v_exp_f32_e32 v157, v157
	v_lshlrev_b32_e32 v146, 16, v170
	v_and_b32_e32 v147, 0xffff0000, v170
	v_lshlrev_b32_e32 v148, 16, v171
	v_and_b32_e32 v149, 0xffff0000, v171
	v_add_f32_e32 v154, 1.0, v154
	v_add_f32_e32 v155, 1.0, v155
	v_add_f32_e32 v156, 1.0, v156
	v_add_f32_e32 v157, 1.0, v157
	v_rcp_f32_e32 v154, v154
	v_rcp_f32_e32 v155, v155
; __device__ __forceinline__ f32x4 acc_i2f(const f32x4 a) { return __builtin_convertvector(__builtin_bit_cast(i32x4, a), f32x4); }
;     __device__ __forceinline__ void operator()(const f32x4 (&acc)[2][2][4][2], const pg8::Unit& u, int wr, int wc, int fr, int fq) const {
;     ...
;                 for (int mm = 0; mm < 2; ++mm) { const int m = 2 * mp + mm, row = row0 + ai * 128 + m * 16; f32x4 ssv = {0.f, 0.f, 0.f, 0.f}; const float sa = (QCLIP / 127.f) * sqrtf(q1v[mm] * (1.f / DM) + EPS);
; #pragma unroll
;                     for (int bj = 0; bj < 2; ++bj) { const size_t off = (size_t)row * DM + col0 + bj * 128;
;                         f32x4 p0, p1, x0, x1; unpack8v(pr[mm][bj], p0, p1); unpack8v(hr[mm][bj], x0, x1);
;                         const f32x4 g0 = acc_i2f(acc[ai][bj][m][0]) * (sb[bj][0] * sa) + bv[bj][0], g1 = acc_i2f(acc[ai][bj][m][1]) * (sb[bj][1] * sa) + bv[bj][1];
;                         const f32x4 h0 = x0 + p0 * sigm4(g0), h1 = x1 + p1 * sigm4(g1);
;                         *(f32x4*)(H + off) = h0; *(f32x4*)(H + off + 4) = h1;
;                         ssv = ssv + h0 * h0; ssv = ssv + h1 * h1; }
;                     float ss = (ssv[0] + ssv[1]) + (ssv[2] + ssv[3]);
;                     ss += __shfl_xor(ss, 16); ss += __shfl_xor(ss, 32);
;                     if (fq == 0) unsafeAtomicAdd(rss3 + row, ss); }
	v_rcp_f32_e32 v156, v156
	v_rcp_f32_e32 v157, v157
	v_lshlrev_b32_e32 v150, 16, v178
	v_and_b32_e32 v151, 0xffff0000, v178
	v_lshlrev_b32_e32 v152, 16, v179
	v_and_b32_e32 v153, 0xffff0000, v179
	v_pk_fma_f32 v[126:127], v[154:155], v[150:151], v[146:147]
	v_pk_fma_f32 v[128:129], v[156:157], v[152:153], v[148:149]
	v_pk_mul_f32 v[194:195], v[126:127], v[126:127]
	v_pk_mul_f32 v[196:197], v[128:129], v[128:129]
	v_cvt_f32_i32_e32 v122, v122
	v_cvt_f32_i32_e32 v123, v123
	v_cvt_f32_i32_e32 v124, v124
	v_cvt_f32_i32_e32 v125, v125
	v_pk_mul_f32 v[142:143], v[226:227], v[188:189] op_sel_hi:[1,0]
	v_pk_mul_f32 v[144:145], v[228:229], v[188:189] op_sel_hi:[1,0]
	v_pk_fma_f32 v[154:155], v[142:143], v[122:123], v[210:211]
	v_pk_fma_f32 v[156:157], v[144:145], v[124:125], v[212:213]
	v_mul_f32_e32 v154, 0xbfb8aa3b, v154
	v_mul_f32_e32 v155, 0xbfb8aa3b, v155
	v_mul_f32_e32 v156, 0xbfb8aa3b, v156
	v_mul_f32_e32 v157, 0xbfb8aa3b, v157
	v_exp_f32_e32 v154, v154
	v_exp_f32_e32 v155, v155
	v_exp_f32_e32 v156, v156
	v_exp_f32_e32 v157, v157
	v_lshlrev_b32_e32 v146, 16, v172
	v_and_b32_e32 v147, 0xffff0000, v172
	v_lshlrev_b32_e32 v148, 16, v173
	v_and_b32_e32 v149, 0xffff0000, v173
	v_add_f32_e32 v154, 1.0, v154
	v_add_f32_e32 v155, 1.0, v155
	v_add_f32_e32 v156, 1.0, v156
	v_add_f32_e32 v157, 1.0, v157
	v_rcp_f32_e32 v154, v154
	v_rcp_f32_e32 v155, v155
	v_rcp_f32_e32 v156, v156
	v_rcp_f32_e32 v157, v157
	v_lshlrev_b32_e32 v150, 16, v180
	v_and_b32_e32 v151, 0xffff0000, v180
	v_lshlrev_b32_e32 v152, 16, v181
	v_and_b32_e32 v153, 0xffff0000, v181
	v_pk_fma_f32 v[122:123], v[154:155], v[150:151], v[146:147]
	v_pk_fma_f32 v[124:125], v[156:157], v[152:153], v[148:149]
	v_pk_fma_f32 v[194:195], v[122:123], v[122:123], v[194:195]
	v_pk_fma_f32 v[196:197], v[124:125], v[124:125], v[196:197]
	v_cvt_f32_i32_e32 v118, v118
	v_cvt_f32_i32_e32 v119, v119
	v_cvt_f32_i32_e32 v120, v120
	v_cvt_f32_i32_e32 v121, v121
	v_pk_mul_f32 v[142:143], v[230:231], v[188:189] op_sel_hi:[1,0]
	v_pk_mul_f32 v[144:145], v[232:233], v[188:189] op_sel_hi:[1,0]
	v_pk_fma_f32 v[154:155], v[142:143], v[118:119], v[214:215]
	v_pk_fma_f32 v[156:157], v[144:145], v[120:121], v[216:217]
	v_mul_f32_e32 v154, 0xbfb8aa3b, v154
	v_mul_f32_e32 v155, 0xbfb8aa3b, v155
	v_mul_f32_e32 v156, 0xbfb8aa3b, v156
	v_mul_f32_e32 v157, 0xbfb8aa3b, v157
	v_exp_f32_e32 v154, v154
	v_exp_f32_e32 v155, v155
	v_exp_f32_e32 v156, v156
	v_exp_f32_e32 v157, v157
	v_lshlrev_b32_e32 v146, 16, v174
	v_and_b32_e32 v147, 0xffff0000, v174
	v_lshlrev_b32_e32 v148, 16, v175
	v_and_b32_e32 v149, 0xffff0000, v175
	v_add_f32_e32 v154, 1.0, v154
	v_add_f32_e32 v155, 1.0, v155
	v_add_f32_e32 v156, 1.0, v156
	v_add_f32_e32 v157, 1.0, v157
	v_rcp_f32_e32 v154, v154
	v_rcp_f32_e32 v155, v155
	v_rcp_f32_e32 v156, v156
	v_rcp_f32_e32 v157, v157
	v_lshlrev_b32_e32 v150, 16, v182
	v_and_b32_e32 v151, 0xffff0000, v182
	v_lshlrev_b32_e32 v152, 16, v183
	v_and_b32_e32 v153, 0xffff0000, v183
	v_pk_fma_f32 v[118:119], v[154:155], v[150:151], v[146:147]
	v_pk_fma_f32 v[120:121], v[156:157], v[152:153], v[148:149]
	v_pk_fma_f32 v[194:195], v[118:119], v[118:119], v[194:195]
	v_pk_fma_f32 v[196:197], v[120:121], v[120:121], v[196:197]
	v_cvt_f32_i32_e32 v114, v114
	v_cvt_f32_i32_e32 v115, v115
	v_cvt_f32_i32_e32 v116, v116
	v_cvt_f32_i32_e32 v117, v117
	v_pk_mul_f32 v[142:143], v[234:235], v[188:189] op_sel_hi:[1,0]
	v_pk_mul_f32 v[144:145], v[236:237], v[188:189] op_sel_hi:[1,0]
	v_pk_fma_f32 v[154:155], v[142:143], v[114:115], v[218:219]
	v_pk_fma_f32 v[156:157], v[144:145], v[116:117], v[220:221]
	v_mul_f32_e32 v154, 0xbfb8aa3b, v154
	v_mul_f32_e32 v155, 0xbfb8aa3b, v155
	v_mul_f32_e32 v156, 0xbfb8aa3b, v156
	v_mul_f32_e32 v157, 0xbfb8aa3b, v157
	v_exp_f32_e32 v154, v154
	v_exp_f32_e32 v155, v155
	v_exp_f32_e32 v156, v156
	v_exp_f32_e32 v157, v157
	v_lshlrev_b32_e32 v146, 16, v176
	v_and_b32_e32 v147, 0xffff0000, v176
	v_lshlrev_b32_e32 v148, 16, v177
	v_and_b32_e32 v149, 0xffff0000, v177
	v_add_f32_e32 v154, 1.0, v154
	v_add_f32_e32 v155, 1.0, v155
	v_add_f32_e32 v156, 1.0, v156
	v_add_f32_e32 v157, 1.0, v157
	v_rcp_f32_e32 v154, v154
	v_rcp_f32_e32 v155, v155
	v_rcp_f32_e32 v156, v156
	v_rcp_f32_e32 v157, v157
	v_lshlrev_b32_e32 v150, 16, v184
	v_and_b32_e32 v151, 0xffff0000, v184
	v_lshlrev_b32_e32 v152, 16, v185
	v_and_b32_e32 v153, 0xffff0000, v185
	v_pk_fma_f32 v[114:115], v[154:155], v[150:151], v[146:147]
	v_pk_fma_f32 v[116:117], v[156:157], v[152:153], v[148:149]
	v_pk_fma_f32 v[194:195], v[114:115], v[114:115], v[194:195]
	v_pk_fma_f32 v[196:197], v[116:117], v[116:117], v[196:197]
	v_add_f32_e32 v194, v194, v195
	v_add_f32_e32 v196, v196, v197
	v_add_f32_e32 v194, v194, v196
	ds_bpermute_b32 v195, v58, v194
	s_waitcnt lgkmcnt(0)
	v_add_f32_e32 v194, v194, v195
	ds_bpermute_b32 v195, v59, v194
	s_waitcnt lgkmcnt(0)
	v_add_f32_e32 v194, v194, v195
	s_and_saveexec_b64 s[32:33], s[6:7]
	global_atomic_add_f32 v54, v194, s[70:71] offset:64
	s_or_b64 exec, exec, s[32:33]
	global_load_dword v67, v54, s[68:69] offset:192
	global_load_dwordx4 v[170:173], v56, s[86:87]
	global_load_dwordx4 v[174:177], v56, s[86:87] offset:256
	global_load_dwordx4 v[178:181], v56, s[88:89] nt
	global_load_dwordx4 v[182:185], v56, s[88:89] offset:256 nt
	s_add_u32 s86, s86, 0xa0000
	s_addc_u32 s87, s87, 0
	s_add_u32 s88, s88, 0xa0000
	s_addc_u32 s89, s89, 0
	s_waitcnt vmcnt(6)
; __device__ __forceinline__ f32x4 acc_i2f(const f32x4 a) { return __builtin_convertvector(__builtin_bit_cast(i32x4, a), f32x4); }
;     __device__ __forceinline__ void operator()(const f32x4 (&acc)[2][2][4][2], const pg8::Unit& u, int wr, int wc, int fr, int fq) const {
;     ...
;                 for (int mm = 0; mm < 2; ++mm) { const int m = 2 * mp + mm, row = row0 + ai * 128 + m * 16; f32x4 ssv = {0.f, 0.f, 0.f, 0.f}; const float sa = (QCLIP / 127.f) * sqrtf(q1v[mm] * (1.f / DM) + EPS);
; #pragma unroll
;                     for (int bj = 0; bj < 2; ++bj) { const size_t off = (size_t)row * DM + col0 + bj * 128;
;                         f32x4 p0, p1, x0, x1; unpack8v(pr[mm][bj], p0, p1); unpack8v(hr[mm][bj], x0, x1);
;                         const f32x4 g0 = acc_i2f(acc[ai][bj][m][0]) * (sb[bj][0] * sa) + bv[bj][0], g1 = acc_i2f(acc[ai][bj][m][1]) * (sb[bj][1] * sa) + bv[bj][1];
;                         const f32x4 h0 = x0 + p0 * sigm4(g0), h1 = x1 + p1 * sigm4(g1);
;                         *(f32x4*)(H + off) = h0; *(f32x4*)(H + off + 4) = h1;
;                         ssv = ssv + h0 * h0; ssv = ssv + h1 * h1; }
;                     float ss = (ssv[0] + ssv[1]) + (ssv[2] + ssv[3]);
;                     ss += __shfl_xor(ss, 16); ss += __shfl_xor(ss, 32);
;                     if (fq == 0) unsafeAtomicAdd(rss3 + row, ss); }
	v_fmamk_f32 v186, v66, 0x39800000, v204
	v_mul_f32_e32 v187, 0x4f800000, v186
	v_cmp_gt_f32_e32 vcc, s67, v186
	s_nop 1
	v_cndmask_b32_e32 v186, v186, v187, vcc
	v_sqrt_f32_e32 v190, v186
	s_nop 0
	v_add_u32_e32 v191, -1, v190
	v_add_u32_e32 v192, 1, v190
	v_fma_f32 v193, -v191, v190, v186
	v_fma_f32 v187, -v192, v190, v186
	v_cmp_ge_f32_e64 s[10:11], 0, v193
	s_nop 1
	v_cndmask_b32_e64 v190, v190, v191, s[10:11]
	v_cmp_lt_f32_e64 s[10:11], 0, v187
	s_nop 1
	v_cndmask_b32_e64 v190, v190, v192, s[10:11]
	v_mul_f32_e32 v191, 0x37800000, v190
	v_cndmask_b32_e32 v190, v190, v191, vcc
	v_cmp_class_f32_e32 vcc, v186, v205
	s_nop 1
	v_cndmask_b32_e32 v186, v190, v186, vcc
	v_mul_f32_e32 v188, 0x3d112245, v186
	v_cvt_f32_i32_e32 v110, v110
	v_cvt_f32_i32_e32 v111, v111
	v_cvt_f32_i32_e32 v112, v112
	v_cvt_f32_i32_e32 v113, v113
	v_pk_mul_f32 v[142:143], v[222:223], v[188:189] op_sel_hi:[1,0]
	v_pk_mul_f32 v[144:145], v[224:225], v[188:189] op_sel_hi:[1,0]
	v_pk_fma_f32 v[154:155], v[142:143], v[110:111], v[206:207]
	v_pk_fma_f32 v[156:157], v[144:145], v[112:113], v[208:209]
	v_mul_f32_e32 v154, 0xbfb8aa3b, v154
	v_mul_f32_e32 v155, 0xbfb8aa3b, v155
	v_mul_f32_e32 v156, 0xbfb8aa3b, v156
	v_mul_f32_e32 v157, 0xbfb8aa3b, v157
	v_exp_f32_e32 v154, v154
	v_exp_f32_e32 v155, v155
	v_exp_f32_e32 v156, v156
	v_exp_f32_e32 v157, v157
	v_lshlrev_b32_e32 v146, 16, v238
	v_and_b32_e32 v147, 0xffff0000, v238
	v_lshlrev_b32_e32 v148, 16, v239
	v_and_b32_e32 v149, 0xffff0000, v239
	v_add_f32_e32 v154, 1.0, v154
	v_add_f32_e32 v155, 1.0, v155
	v_add_f32_e32 v156, 1.0, v156
	v_add_f32_e32 v157, 1.0, v157
	v_rcp_f32_e32 v154, v154
	v_rcp_f32_e32 v155, v155
	v_rcp_f32_e32 v156, v156
	v_rcp_f32_e32 v157, v157
	v_lshlrev_b32_e32 v150, 16, v246
	v_and_b32_e32 v151, 0xffff0000, v246
	v_lshlrev_b32_e32 v152, 16, v247
	v_and_b32_e32 v153, 0xffff0000, v247
	v_pk_fma_f32 v[110:111], v[154:155], v[150:151], v[146:147]
	v_pk_fma_f32 v[112:113], v[156:157], v[152:153], v[148:149]
	v_pk_mul_f32 v[194:195], v[110:111], v[110:111]
	v_pk_mul_f32 v[196:197], v[112:113], v[112:113]
	v_cvt_f32_i32_e32 v106, v106
	v_cvt_f32_i32_e32 v107, v107
	v_cvt_f32_i32_e32 v108, v108
	v_cvt_f32_i32_e32 v109, v109
	v_pk_mul_f32 v[142:143], v[226:227], v[188:189] op_sel_hi:[1,0]
	v_pk_mul_f32 v[144:145], v[228:229], v[188:189] op_sel_hi:[1,0]
	v_pk_fma_f32 v[154:155], v[142:143], v[106:107], v[210:211]
	v_pk_fma_f32 v[156:157], v[144:145], v[108:109], v[212:213]
	v_mul_f32_e32 v154, 0xbfb8aa3b, v154
	v_mul_f32_e32 v155, 0xbfb8aa3b, v155
	v_mul_f32_e32 v156, 0xbfb8aa3b, v156
	v_mul_f32_e32 v157, 0xbfb8aa3b, v157
	v_exp_f32_e32 v154, v154
	v_exp_f32_e32 v155, v155
	v_exp_f32_e32 v156, v156
	v_exp_f32_e32 v157, v157
	v_lshlrev_b32_e32 v146, 16, v240
	v_and_b32_e32 v147, 0xffff0000, v240
	v_lshlrev_b32_e32 v148, 16, v241
	v_and_b32_e32 v149, 0xffff0000, v241
	v_add_f32_e32 v154, 1.0, v154
	v_add_f32_e32 v155, 1.0, v155
	v_add_f32_e32 v156, 1.0, v156
	v_add_f32_e32 v157, 1.0, v157
	v_rcp_f32_e32 v154, v154
	v_rcp_f32_e32 v155, v155
	v_rcp_f32_e32 v156, v156
	v_rcp_f32_e32 v157, v157
	v_lshlrev_b32_e32 v150, 16, v248
	v_and_b32_e32 v151, 0xffff0000, v248
	v_lshlrev_b32_e32 v152, 16, v249
	v_and_b32_e32 v153, 0xffff0000, v249
	v_pk_fma_f32 v[106:107], v[154:155], v[150:151], v[146:147]
	v_pk_fma_f32 v[108:109], v[156:157], v[152:153], v[148:149]
	v_pk_fma_f32 v[194:195], v[106:107], v[106:107], v[194:195]
	v_pk_fma_f32 v[196:197], v[108:109], v[108:109], v[196:197]
	v_cvt_f32_i32_e32 v102, v102
	v_cvt_f32_i32_e32 v103, v103
	v_cvt_f32_i32_e32 v104, v104
	v_cvt_f32_i32_e32 v105, v105
	v_pk_mul_f32 v[142:143], v[230:231], v[188:189] op_sel_hi:[1,0]
	v_pk_mul_f32 v[144:145], v[232:233], v[188:189] op_sel_hi:[1,0]
	v_pk_fma_f32 v[154:155], v[142:143], v[102:103], v[214:215]
	v_pk_fma_f32 v[156:157], v[144:145], v[104:105], v[216:217]
	v_mul_f32_e32 v154, 0xbfb8aa3b, v154
	v_mul_f32_e32 v155, 0xbfb8aa3b, v155
	v_mul_f32_e32 v156, 0xbfb8aa3b, v156
	v_mul_f32_e32 v157, 0xbfb8aa3b, v157
	v_exp_f32_e32 v154, v154
	v_exp_f32_e32 v155, v155
	v_exp_f32_e32 v156, v156
	v_exp_f32_e32 v157, v157
	v_lshlrev_b32_e32 v146, 16, v242
	v_and_b32_e32 v147, 0xffff0000, v242
	v_lshlrev_b32_e32 v148, 16, v243
	v_and_b32_e32 v149, 0xffff0000, v243
	v_add_f32_e32 v154, 1.0, v154
	v_add_f32_e32 v155, 1.0, v155
	v_add_f32_e32 v156, 1.0, v156
	v_add_f32_e32 v157, 1.0, v157
	v_rcp_f32_e32 v154, v154
	v_rcp_f32_e32 v155, v155
	v_rcp_f32_e32 v156, v156
	v_rcp_f32_e32 v157, v157
	v_lshlrev_b32_e32 v150, 16, v250
	v_and_b32_e32 v151, 0xffff0000, v250
	v_lshlrev_b32_e32 v152, 16, v251
	v_and_b32_e32 v153, 0xffff0000, v251
	v_pk_fma_f32 v[102:103], v[154:155], v[150:151], v[146:147]
	v_pk_fma_f32 v[104:105], v[156:157], v[152:153], v[148:149]
	v_pk_fma_f32 v[194:195], v[102:103], v[102:103], v[194:195]
	v_pk_fma_f32 v[196:197], v[104:105], v[104:105], v[196:197]
	v_cvt_f32_i32_e32 v98, v98
	v_cvt_f32_i32_e32 v99, v99
	v_cvt_f32_i32_e32 v100, v100
	v_cvt_f32_i32_e32 v101, v101
	v_pk_mul_f32 v[142:143], v[234:235], v[188:189] op_sel_hi:[1,0]
	v_pk_mul_f32 v[144:145], v[236:237], v[188:189] op_sel_hi:[1,0]
	v_pk_fma_f32 v[154:155], v[142:143], v[98:99], v[218:219]
	v_pk_fma_f32 v[156:157], v[144:145], v[100:101], v[220:221]
	v_mul_f32_e32 v154, 0xbfb8aa3b, v154
	v_mul_f32_e32 v155, 0xbfb8aa3b, v155
	v_mul_f32_e32 v156, 0xbfb8aa3b, v156
	v_mul_f32_e32 v157, 0xbfb8aa3b, v157
	v_exp_f32_e32 v154, v154
	v_exp_f32_e32 v155, v155
	v_exp_f32_e32 v156, v156
	v_exp_f32_e32 v157, v157
	v_lshlrev_b32_e32 v146, 16, v244
	v_and_b32_e32 v147, 0xffff0000, v244
	v_lshlrev_b32_e32 v148, 16, v245
	v_and_b32_e32 v149, 0xffff0000, v245
	v_add_f32_e32 v154, 1.0, v154
	v_add_f32_e32 v155, 1.0, v155
	v_add_f32_e32 v156, 1.0, v156
	v_add_f32_e32 v157, 1.0, v157
	v_rcp_f32_e32 v154, v154
	v_rcp_f32_e32 v155, v155
	v_rcp_f32_e32 v156, v156
	v_rcp_f32_e32 v157, v157
	v_lshlrev_b32_e32 v150, 16, v252
	v_and_b32_e32 v151, 0xffff0000, v252
	v_lshlrev_b32_e32 v152, 16, v253
	v_and_b32_e32 v153, 0xffff0000, v253
	v_pk_fma_f32 v[98:99], v[154:155], v[150:151], v[146:147]
	v_pk_fma_f32 v[100:101], v[156:157], v[152:153], v[148:149]
	v_pk_fma_f32 v[194:195], v[98:99], v[98:99], v[194:195]
	v_pk_fma_f32 v[196:197], v[100:101], v[100:101], v[196:197]
	v_add_f32_e32 v194, v194, v195
	v_add_f32_e32 v196, v196, v197
	v_add_f32_e32 v194, v194, v196
	ds_bpermute_b32 v195, v58, v194
	s_waitcnt lgkmcnt(0)
; __device__ __forceinline__ f32x4 acc_i2f(const f32x4 a) { return __builtin_convertvector(__builtin_bit_cast(i32x4, a), f32x4); }
;     __device__ __forceinline__ void operator()(const f32x4 (&acc)[2][2][4][2], const pg8::Unit& u, int wr, int wc, int fr, int fq) const {
;     ...
;                 for (int mm = 0; mm < 2; ++mm) { const int m = 2 * mp + mm, row = row0 + ai * 128 + m * 16; f32x4 ssv = {0.f, 0.f, 0.f, 0.f}; const float sa = (QCLIP / 127.f) * sqrtf(q1v[mm] * (1.f / DM) + EPS);
; #pragma unroll
;                     for (int bj = 0; bj < 2; ++bj) { const size_t off = (size_t)row * DM + col0 + bj * 128;
;                         f32x4 p0, p1, x0, x1; unpack8v(pr[mm][bj], p0, p1); unpack8v(hr[mm][bj], x0, x1);
;                         const f32x4 g0 = acc_i2f(acc[ai][bj][m][0]) * (sb[bj][0] * sa) + bv[bj][0], g1 = acc_i2f(acc[ai][bj][m][1]) * (sb[bj][1] * sa) + bv[bj][1];
;                         const f32x4 h0 = x0 + p0 * sigm4(g0), h1 = x1 + p1 * sigm4(g1);
;                         *(f32x4*)(H + off) = h0; *(f32x4*)(H + off + 4) = h1;
;                         ssv = ssv + h0 * h0; ssv = ssv + h1 * h1; }
;                     float ss = (ssv[0] + ssv[1]) + (ssv[2] + ssv[3]);
;                     ss += __shfl_xor(ss, 16); ss += __shfl_xor(ss, 32);
;                     if (fq == 0) unsafeAtomicAdd(rss3 + row, ss); }
	v_add_f32_e32 v194, v194, v195
	ds_bpermute_b32 v195, v59, v194
	s_waitcnt lgkmcnt(0)
	v_add_f32_e32 v194, v194, v195
	s_and_saveexec_b64 s[32:33], s[6:7]
	global_atomic_add_f32 v54, v194, s[70:71] offset:128
	s_or_b64 exec, exec, s[32:33]
	global_load_dword v66, v54, s[68:69] offset:512
	global_load_dwordx4 v[238:241], v56, s[86:87]
	global_load_dwordx4 v[242:245], v56, s[86:87] offset:256
	global_load_dwordx4 v[246:249], v56, s[88:89] nt
	global_load_dwordx4 v[250:253], v56, s[88:89] offset:256 nt
	s_add_u32 s86, s86, 0x20000
	s_addc_u32 s87, s87, 0
	s_add_u32 s88, s88, 0x20000
	s_addc_u32 s89, s89, 0
	s_waitcnt vmcnt(6)
	v_fmamk_f32 v186, v67, 0x39800000, v204
	v_mul_f32_e32 v187, 0x4f800000, v186
	v_cmp_gt_f32_e32 vcc, s67, v186
	s_nop 1
	v_cndmask_b32_e32 v186, v186, v187, vcc
	v_sqrt_f32_e32 v190, v186
	s_nop 0
	v_add_u32_e32 v191, -1, v190
	v_add_u32_e32 v192, 1, v190
	v_fma_f32 v193, -v191, v190, v186
	v_fma_f32 v187, -v192, v190, v186
	v_cmp_ge_f32_e64 s[10:11], 0, v193
	s_nop 1
	v_cndmask_b32_e64 v190, v190, v191, s[10:11]
	v_cmp_lt_f32_e64 s[10:11], 0, v187
	s_nop 1
	v_cndmask_b32_e64 v190, v190, v192, s[10:11]
	v_mul_f32_e32 v191, 0x37800000, v190
	v_cndmask_b32_e32 v190, v190, v191, vcc
	v_cmp_class_f32_e32 vcc, v186, v205
	s_nop 1
	v_cndmask_b32_e32 v186, v190, v186, vcc
	v_mul_f32_e32 v188, 0x3d112245, v186
	v_cvt_f32_i32_e32 v94, v94
	v_cvt_f32_i32_e32 v95, v95
	v_cvt_f32_i32_e32 v96, v96
	v_cvt_f32_i32_e32 v97, v97
	v_pk_mul_f32 v[142:143], v[222:223], v[188:189] op_sel_hi:[1,0]
	v_pk_mul_f32 v[144:145], v[224:225], v[188:189] op_sel_hi:[1,0]
	v_pk_fma_f32 v[154:155], v[142:143], v[94:95], v[206:207]
	v_pk_fma_f32 v[156:157], v[144:145], v[96:97], v[208:209]
	v_mul_f32_e32 v154, 0xbfb8aa3b, v154
	v_mul_f32_e32 v155, 0xbfb8aa3b, v155
	v_mul_f32_e32 v156, 0xbfb8aa3b, v156
	v_mul_f32_e32 v157, 0xbfb8aa3b, v157
	v_exp_f32_e32 v154, v154
	v_exp_f32_e32 v155, v155
	v_exp_f32_e32 v156, v156
	v_exp_f32_e32 v157, v157
	v_lshlrev_b32_e32 v146, 16, v170
	v_and_b32_e32 v147, 0xffff0000, v170
	v_lshlrev_b32_e32 v148, 16, v171
	v_and_b32_e32 v149, 0xffff0000, v171
	v_add_f32_e32 v154, 1.0, v154
	v_add_f32_e32 v155, 1.0, v155
	v_add_f32_e32 v156, 1.0, v156
	v_add_f32_e32 v157, 1.0, v157
	v_rcp_f32_e32 v154, v154
	v_rcp_f32_e32 v155, v155
	v_rcp_f32_e32 v156, v156
	v_rcp_f32_e32 v157, v157
	v_lshlrev_b32_e32 v150, 16, v178
	v_and_b32_e32 v151, 0xffff0000, v178
	v_lshlrev_b32_e32 v152, 16, v179
	v_and_b32_e32 v153, 0xffff0000, v179
	v_pk_fma_f32 v[94:95], v[154:155], v[150:151], v[146:147]
	v_pk_fma_f32 v[96:97], v[156:157], v[152:153], v[148:149]
	v_pk_mul_f32 v[194:195], v[94:95], v[94:95]
	v_pk_mul_f32 v[196:197], v[96:97], v[96:97]
	v_cvt_f32_i32_e32 v90, v90
	v_cvt_f32_i32_e32 v91, v91
	v_cvt_f32_i32_e32 v92, v92
	v_cvt_f32_i32_e32 v93, v93
	v_pk_mul_f32 v[142:143], v[226:227], v[188:189] op_sel_hi:[1,0]
	v_pk_mul_f32 v[144:145], v[228:229], v[188:189] op_sel_hi:[1,0]
	v_pk_fma_f32 v[154:155], v[142:143], v[90:91], v[210:211]
	v_pk_fma_f32 v[156:157], v[144:145], v[92:93], v[212:213]
	v_mul_f32_e32 v154, 0xbfb8aa3b, v154
	v_mul_f32_e32 v155, 0xbfb8aa3b, v155
	v_mul_f32_e32 v156, 0xbfb8aa3b, v156
	v_mul_f32_e32 v157, 0xbfb8aa3b, v157
	v_exp_f32_e32 v154, v154
	v_exp_f32_e32 v155, v155
	v_exp_f32_e32 v156, v156
	v_exp_f32_e32 v157, v157
	v_lshlrev_b32_e32 v146, 16, v172
	v_and_b32_e32 v147, 0xffff0000, v172
	v_lshlrev_b32_e32 v148, 16, v173
	v_and_b32_e32 v149, 0xffff0000, v173
	v_add_f32_e32 v154, 1.0, v154
	v_add_f32_e32 v155, 1.0, v155
	v_add_f32_e32 v156, 1.0, v156
	v_add_f32_e32 v157, 1.0, v157
	v_rcp_f32_e32 v154, v154
	v_rcp_f32_e32 v155, v155
	v_rcp_f32_e32 v156, v156
	v_rcp_f32_e32 v157, v157
	v_lshlrev_b32_e32 v150, 16, v180
	v_and_b32_e32 v151, 0xffff0000, v180
	v_lshlrev_b32_e32 v152, 16, v181
	v_and_b32_e32 v153, 0xffff0000, v181
	v_pk_fma_f32 v[90:91], v[154:155], v[150:151], v[146:147]
	v_pk_fma_f32 v[92:93], v[156:157], v[152:153], v[148:149]
	v_pk_fma_f32 v[194:195], v[90:91], v[90:91], v[194:195]
	v_pk_fma_f32 v[196:197], v[92:93], v[92:93], v[196:197]
	v_cvt_f32_i32_e32 v86, v86
	v_cvt_f32_i32_e32 v87, v87
	v_cvt_f32_i32_e32 v88, v88
	v_cvt_f32_i32_e32 v89, v89
	v_pk_mul_f32 v[142:143], v[230:231], v[188:189] op_sel_hi:[1,0]
	v_pk_mul_f32 v[144:145], v[232:233], v[188:189] op_sel_hi:[1,0]
	v_pk_fma_f32 v[154:155], v[142:143], v[86:87], v[214:215]
	v_pk_fma_f32 v[156:157], v[144:145], v[88:89], v[216:217]
	v_mul_f32_e32 v154, 0xbfb8aa3b, v154
	v_mul_f32_e32 v155, 0xbfb8aa3b, v155
	v_mul_f32_e32 v156, 0xbfb8aa3b, v156
	v_mul_f32_e32 v157, 0xbfb8aa3b, v157
	v_exp_f32_e32 v154, v154
	v_exp_f32_e32 v155, v155
	v_exp_f32_e32 v156, v156
	v_exp_f32_e32 v157, v157
	v_lshlrev_b32_e32 v146, 16, v174
	v_and_b32_e32 v147, 0xffff0000, v174
	v_lshlrev_b32_e32 v148, 16, v175
	v_and_b32_e32 v149, 0xffff0000, v175
	v_add_f32_e32 v154, 1.0, v154
	v_add_f32_e32 v155, 1.0, v155
	v_add_f32_e32 v156, 1.0, v156
	v_add_f32_e32 v157, 1.0, v157
	v_rcp_f32_e32 v154, v154
	v_rcp_f32_e32 v155, v155
	v_rcp_f32_e32 v156, v156
	v_rcp_f32_e32 v157, v157
	v_lshlrev_b32_e32 v150, 16, v182
	v_and_b32_e32 v151, 0xffff0000, v182
	v_lshlrev_b32_e32 v152, 16, v183
	v_and_b32_e32 v153, 0xffff0000, v183
	v_pk_fma_f32 v[86:87], v[154:155], v[150:151], v[146:147]
	v_pk_fma_f32 v[88:89], v[156:157], v[152:153], v[148:149]
	v_pk_fma_f32 v[194:195], v[86:87], v[86:87], v[194:195]
	v_pk_fma_f32 v[196:197], v[88:89], v[88:89], v[196:197]
	v_cvt_f32_i32_e32 v82, v82
	v_cvt_f32_i32_e32 v83, v83
	v_cvt_f32_i32_e32 v84, v84
	v_cvt_f32_i32_e32 v85, v85
	v_pk_mul_f32 v[142:143], v[234:235], v[188:189] op_sel_hi:[1,0]
	v_pk_mul_f32 v[144:145], v[236:237], v[188:189] op_sel_hi:[1,0]
	v_pk_fma_f32 v[154:155], v[142:143], v[82:83], v[218:219]
	v_pk_fma_f32 v[156:157], v[144:145], v[84:85], v[220:221]
	v_mul_f32_e32 v154, 0xbfb8aa3b, v154
	v_mul_f32_e32 v155, 0xbfb8aa3b, v155
	v_mul_f32_e32 v156, 0xbfb8aa3b, v156
	v_mul_f32_e32 v157, 0xbfb8aa3b, v157
	v_exp_f32_e32 v154, v154
	v_exp_f32_e32 v155, v155
	v_exp_f32_e32 v156, v156
	v_exp_f32_e32 v157, v157
	v_lshlrev_b32_e32 v146, 16, v176
	v_and_b32_e32 v147, 0xffff0000, v176
	v_lshlrev_b32_e32 v148, 16, v177
	v_and_b32_e32 v149, 0xffff0000, v177
	v_add_f32_e32 v154, 1.0, v154
	v_add_f32_e32 v155, 1.0, v155
	v_add_f32_e32 v156, 1.0, v156
	v_add_f32_e32 v157, 1.0, v157
	v_rcp_f32_e32 v154, v154
	v_rcp_f32_e32 v155, v155
	v_rcp_f32_e32 v156, v156
	v_rcp_f32_e32 v157, v157
	v_lshlrev_b32_e32 v150, 16, v184
	v_and_b32_e32 v151, 0xffff0000, v184
	v_lshlrev_b32_e32 v152, 16, v185
	v_and_b32_e32 v153, 0xffff0000, v185
	v_pk_fma_f32 v[82:83], v[154:155], v[150:151], v[146:147]
	v_pk_fma_f32 v[84:85], v[156:157], v[152:153], v[148:149]
	v_pk_fma_f32 v[194:195], v[82:83], v[82:83], v[194:195]
	v_pk_fma_f32 v[196:197], v[84:85], v[84:85], v[196:197]
	v_add_f32_e32 v194, v194, v195
	v_add_f32_e32 v196, v196, v197
	v_add_f32_e32 v194, v194, v196
	ds_bpermute_b32 v195, v58, v194
	s_waitcnt lgkmcnt(0)
; __device__ __forceinline__ f32x4 acc_i2f(const f32x4 a) { return __builtin_convertvector(__builtin_bit_cast(i32x4, a), f32x4); }
;     __device__ __forceinline__ void operator()(const f32x4 (&acc)[2][2][4][2], const pg8::Unit& u, int wr, int wc, int fr, int fq) const {
;     ...
;                 u32x4 hr[2][2], pr[2][2]; float q1v[2];
; #pragma unroll
;                 for (int mm = 0; mm < 2; ++mm) { const int row = row0 + ai * 128 + (2 * mp + mm) * 16; q1v[mm] = rss1[row];
; #pragma unroll
;                     for (int bj = 0; bj < 2; ++bj) { const size_t off = (size_t)row * DM + col0 + bj * 128; hr[mm][bj] = *(const u32x4*)(HB + off); pr[mm][bj] = *(const u32x4*)(PP + off); } }
; #pragma unroll
;                 for (int mm = 0; mm < 2; ++mm) { const int m = 2 * mp + mm, row = row0 + ai * 128 + m * 16; f32x4 ssv = {0.f, 0.f, 0.f, 0.f}; const float sa = (QCLIP / 127.f) * sqrtf(q1v[mm] * (1.f / DM) + EPS);
; #pragma unroll
;                     for (int bj = 0; bj < 2; ++bj) { const size_t off = (size_t)row * DM + col0 + bj * 128;
;                         f32x4 p0, p1, x0, x1; unpack8v(pr[mm][bj], p0, p1); unpack8v(hr[mm][bj], x0, x1);
;                         const f32x4 g0 = acc_i2f(acc[ai][bj][m][0]) * (sb[bj][0] * sa) + bv[bj][0], g1 = acc_i2f(acc[ai][bj][m][1]) * (sb[bj][1] * sa) + bv[bj][1];
;                         const f32x4 h0 = x0 + p0 * sigm4(g0), h1 = x1 + p1 * sigm4(g1);
;                         *(f32x4*)(H + off) = h0; *(f32x4*)(H + off + 4) = h1;
;                         ssv = ssv + h0 * h0; ssv = ssv + h1 * h1; }
;                     float ss = (ssv[0] + ssv[1]) + (ssv[2] + ssv[3]);
;                     ss += __shfl_xor(ss, 16); ss += __shfl_xor(ss, 32);
;                     if (fq == 0) unsafeAtomicAdd(rss3 + row, ss); }
	v_add_f32_e32 v194, v194, v195
	ds_bpermute_b32 v195, v59, v194
	s_waitcnt lgkmcnt(0)
	v_add_f32_e32 v194, v194, v195
	s_and_saveexec_b64 s[32:33], s[6:7]
	global_atomic_add_f32 v54, v194, s[70:71] offset:192
	s_or_b64 exec, exec, s[32:33]
	global_load_dword v67, v54, s[68:69] offset:576
	global_load_dwordx4 v[170:173], v56, s[86:87]
	global_load_dwordx4 v[174:177], v56, s[86:87] offset:256
	global_load_dwordx4 v[178:181], v56, s[88:89] nt
	global_load_dwordx4 v[182:185], v56, s[88:89] offset:256 nt
	s_add_u32 s86, s86, 0x20000
	s_addc_u32 s87, s87, 0
	s_add_u32 s88, s88, 0x20000
	s_addc_u32 s89, s89, 0
	s_waitcnt vmcnt(6)
	v_fmamk_f32 v186, v66, 0x39800000, v204
	v_mul_f32_e32 v187, 0x4f800000, v186
	v_cmp_gt_f32_e32 vcc, s67, v186
	s_nop 1
	v_cndmask_b32_e32 v186, v186, v187, vcc
	v_sqrt_f32_e32 v190, v186
	s_nop 0
	v_add_u32_e32 v191, -1, v190
	v_add_u32_e32 v192, 1, v190
	v_fma_f32 v193, -v191, v190, v186
	v_fma_f32 v187, -v192, v190, v186
	v_cmp_ge_f32_e64 s[10:11], 0, v193
	s_nop 1
	v_cndmask_b32_e64 v190, v190, v191, s[10:11]
	v_cmp_lt_f32_e64 s[10:11], 0, v187
	s_nop 1
	v_cndmask_b32_e64 v190, v190, v192, s[10:11]
	v_mul_f32_e32 v191, 0x37800000, v190
	v_cndmask_b32_e32 v190, v190, v191, vcc
	v_cmp_class_f32_e32 vcc, v186, v205
	s_nop 1
	v_cndmask_b32_e32 v186, v190, v186, vcc
	v_mul_f32_e32 v188, 0x3d112245, v186
	v_cvt_f32_i32_e32 v78, v78
	v_cvt_f32_i32_e32 v79, v79
	v_cvt_f32_i32_e32 v80, v80
	v_cvt_f32_i32_e32 v81, v81
	v_pk_mul_f32 v[142:143], v[222:223], v[188:189] op_sel_hi:[1,0]
	v_pk_mul_f32 v[144:145], v[224:225], v[188:189] op_sel_hi:[1,0]
	v_pk_fma_f32 v[154:155], v[142:143], v[78:79], v[206:207]
	v_pk_fma_f32 v[156:157], v[144:145], v[80:81], v[208:209]
	v_mul_f32_e32 v154, 0xbfb8aa3b, v154
	v_mul_f32_e32 v155, 0xbfb8aa3b, v155
	v_mul_f32_e32 v156, 0xbfb8aa3b, v156
	v_mul_f32_e32 v157, 0xbfb8aa3b, v157
	v_exp_f32_e32 v154, v154
	v_exp_f32_e32 v155, v155
	v_exp_f32_e32 v156, v156
	v_exp_f32_e32 v157, v157
	v_lshlrev_b32_e32 v146, 16, v238
	v_and_b32_e32 v147, 0xffff0000, v238
	v_lshlrev_b32_e32 v148, 16, v239
	v_and_b32_e32 v149, 0xffff0000, v239
	v_add_f32_e32 v154, 1.0, v154
	v_add_f32_e32 v155, 1.0, v155
	v_add_f32_e32 v156, 1.0, v156
	v_add_f32_e32 v157, 1.0, v157
	v_rcp_f32_e32 v154, v154
	v_rcp_f32_e32 v155, v155
	v_rcp_f32_e32 v156, v156
	v_rcp_f32_e32 v157, v157
	v_lshlrev_b32_e32 v150, 16, v246
	v_and_b32_e32 v151, 0xffff0000, v246
	v_lshlrev_b32_e32 v152, 16, v247
	v_and_b32_e32 v153, 0xffff0000, v247
	v_pk_fma_f32 v[78:79], v[154:155], v[150:151], v[146:147]
	v_pk_fma_f32 v[80:81], v[156:157], v[152:153], v[148:149]
	v_pk_mul_f32 v[194:195], v[78:79], v[78:79]
	v_pk_mul_f32 v[196:197], v[80:81], v[80:81]
	v_cvt_f32_i32_e32 v74, v74
	v_cvt_f32_i32_e32 v75, v75
	v_cvt_f32_i32_e32 v76, v76
	v_cvt_f32_i32_e32 v77, v77
	v_pk_mul_f32 v[142:143], v[226:227], v[188:189] op_sel_hi:[1,0]
	v_pk_mul_f32 v[144:145], v[228:229], v[188:189] op_sel_hi:[1,0]
	v_pk_fma_f32 v[154:155], v[142:143], v[74:75], v[210:211]
	v_pk_fma_f32 v[156:157], v[144:145], v[76:77], v[212:213]
	v_mul_f32_e32 v154, 0xbfb8aa3b, v154
	v_mul_f32_e32 v155, 0xbfb8aa3b, v155
	v_mul_f32_e32 v156, 0xbfb8aa3b, v156
	v_mul_f32_e32 v157, 0xbfb8aa3b, v157
	v_exp_f32_e32 v154, v154
	v_exp_f32_e32 v155, v155
	v_exp_f32_e32 v156, v156
	v_exp_f32_e32 v157, v157
	v_lshlrev_b32_e32 v146, 16, v240
	v_and_b32_e32 v147, 0xffff0000, v240
	v_lshlrev_b32_e32 v148, 16, v241
	v_and_b32_e32 v149, 0xffff0000, v241
	v_add_f32_e32 v154, 1.0, v154
	v_add_f32_e32 v155, 1.0, v155
	v_add_f32_e32 v156, 1.0, v156
	v_add_f32_e32 v157, 1.0, v157
	v_rcp_f32_e32 v154, v154
	v_rcp_f32_e32 v155, v155
	v_rcp_f32_e32 v156, v156
	v_rcp_f32_e32 v157, v157
	v_lshlrev_b32_e32 v150, 16, v248
	v_and_b32_e32 v151, 0xffff0000, v248
	v_lshlrev_b32_e32 v152, 16, v249
	v_and_b32_e32 v153, 0xffff0000, v249
	v_pk_fma_f32 v[74:75], v[154:155], v[150:151], v[146:147]
	v_pk_fma_f32 v[76:77], v[156:157], v[152:153], v[148:149]
	v_pk_fma_f32 v[194:195], v[74:75], v[74:75], v[194:195]
	v_pk_fma_f32 v[196:197], v[76:77], v[76:77], v[196:197]
	v_cvt_f32_i32_e32 v70, v70
	v_cvt_f32_i32_e32 v71, v71
	v_cvt_f32_i32_e32 v72, v72
	v_cvt_f32_i32_e32 v73, v73
	v_pk_mul_f32 v[142:143], v[230:231], v[188:189] op_sel_hi:[1,0]
	v_pk_mul_f32 v[144:145], v[232:233], v[188:189] op_sel_hi:[1,0]
	v_pk_fma_f32 v[154:155], v[142:143], v[70:71], v[214:215]
	v_pk_fma_f32 v[156:157], v[144:145], v[72:73], v[216:217]
	v_mul_f32_e32 v154, 0xbfb8aa3b, v154
	v_mul_f32_e32 v155, 0xbfb8aa3b, v155
	v_mul_f32_e32 v156, 0xbfb8aa3b, v156
	v_mul_f32_e32 v157, 0xbfb8aa3b, v157
	v_exp_f32_e32 v154, v154
	v_exp_f32_e32 v155, v155
	v_exp_f32_e32 v156, v156
	v_exp_f32_e32 v157, v157
	v_lshlrev_b32_e32 v146, 16, v242
	v_and_b32_e32 v147, 0xffff0000, v242
	v_lshlrev_b32_e32 v148, 16, v243
	v_and_b32_e32 v149, 0xffff0000, v243
	v_add_f32_e32 v154, 1.0, v154
	v_add_f32_e32 v155, 1.0, v155
	v_add_f32_e32 v156, 1.0, v156
	v_add_f32_e32 v157, 1.0, v157
	v_rcp_f32_e32 v154, v154
	v_rcp_f32_e32 v155, v155
	v_rcp_f32_e32 v156, v156
	v_rcp_f32_e32 v157, v157
	v_lshlrev_b32_e32 v150, 16, v250
	v_and_b32_e32 v151, 0xffff0000, v250
	v_lshlrev_b32_e32 v152, 16, v251
	v_and_b32_e32 v153, 0xffff0000, v251
	v_pk_fma_f32 v[70:71], v[154:155], v[150:151], v[146:147]
	v_pk_fma_f32 v[72:73], v[156:157], v[152:153], v[148:149]
	v_pk_fma_f32 v[194:195], v[70:71], v[70:71], v[194:195]
	v_pk_fma_f32 v[196:197], v[72:73], v[72:73], v[196:197]
	v_cvt_f32_i32_e32 v62, v62
	v_cvt_f32_i32_e32 v63, v63
	v_cvt_f32_i32_e32 v64, v64
	v_cvt_f32_i32_e32 v65, v65
	v_pk_mul_f32 v[142:143], v[234:235], v[188:189] op_sel_hi:[1,0]
	v_pk_mul_f32 v[144:145], v[236:237], v[188:189] op_sel_hi:[1,0]
	v_pk_fma_f32 v[154:155], v[142:143], v[62:63], v[218:219]
	v_pk_fma_f32 v[156:157], v[144:145], v[64:65], v[220:221]
	v_mul_f32_e32 v154, 0xbfb8aa3b, v154
	v_mul_f32_e32 v155, 0xbfb8aa3b, v155
	v_mul_f32_e32 v156, 0xbfb8aa3b, v156
	v_mul_f32_e32 v157, 0xbfb8aa3b, v157
	v_exp_f32_e32 v154, v154
	v_exp_f32_e32 v155, v155
	v_exp_f32_e32 v156, v156
	v_exp_f32_e32 v157, v157
	v_lshlrev_b32_e32 v146, 16, v244
	v_and_b32_e32 v147, 0xffff0000, v244
	v_lshlrev_b32_e32 v148, 16, v245
	v_and_b32_e32 v149, 0xffff0000, v245
	v_add_f32_e32 v154, 1.0, v154
	v_add_f32_e32 v155, 1.0, v155
	v_add_f32_e32 v156, 1.0, v156
	v_add_f32_e32 v157, 1.0, v157
	v_rcp_f32_e32 v154, v154
	v_rcp_f32_e32 v155, v155
	v_rcp_f32_e32 v156, v156
	v_rcp_f32_e32 v157, v157
	v_lshlrev_b32_e32 v150, 16, v252
	v_and_b32_e32 v151, 0xffff0000, v252
	v_lshlrev_b32_e32 v152, 16, v253
	v_and_b32_e32 v153, 0xffff0000, v253
	v_pk_fma_f32 v[62:63], v[154:155], v[150:151], v[146:147]
	v_pk_fma_f32 v[64:65], v[156:157], v[152:153], v[148:149]
	v_pk_fma_f32 v[194:195], v[62:63], v[62:63], v[194:195]
	v_pk_fma_f32 v[196:197], v[64:65], v[64:65], v[196:197]
	v_add_f32_e32 v194, v194, v195
	v_add_f32_e32 v196, v196, v197
	v_add_f32_e32 v194, v194, v196
	ds_bpermute_b32 v195, v58, v194
	s_waitcnt lgkmcnt(0)
; __device__ __forceinline__ f32x4 acc_i2f(const f32x4 a) { return __builtin_convertvector(__builtin_bit_cast(i32x4, a), f32x4); }
;     __device__ __forceinline__ void operator()(const f32x4 (&acc)[2][2][4][2], const pg8::Unit& u, int wr, int wc, int fr, int fq) const {
;     ...
;                 u32x4 hr[2][2], pr[2][2]; float q1v[2];
; #pragma unroll
;                 for (int mm = 0; mm < 2; ++mm) { const int row = row0 + ai * 128 + (2 * mp + mm) * 16; q1v[mm] = rss1[row];
; #pragma unroll
;                     for (int bj = 0; bj < 2; ++bj) { const size_t off = (size_t)row * DM + col0 + bj * 128; hr[mm][bj] = *(const u32x4*)(HB + off); pr[mm][bj] = *(const u32x4*)(PP + off); } }
; #pragma unroll
;                 for (int mm = 0; mm < 2; ++mm) { const int m = 2 * mp + mm, row = row0 + ai * 128 + m * 16; f32x4 ssv = {0.f, 0.f, 0.f, 0.f}; const float sa = (QCLIP / 127.f) * sqrtf(q1v[mm] * (1.f / DM) + EPS);
; #pragma unroll
;                     for (int bj = 0; bj < 2; ++bj) { const size_t off = (size_t)row * DM + col0 + bj * 128;
;                         f32x4 p0, p1, x0, x1; unpack8v(pr[mm][bj], p0, p1); unpack8v(hr[mm][bj], x0, x1);
;                         const f32x4 g0 = acc_i2f(acc[ai][bj][m][0]) * (sb[bj][0] * sa) + bv[bj][0], g1 = acc_i2f(acc[ai][bj][m][1]) * (sb[bj][1] * sa) + bv[bj][1];
;                         const f32x4 h0 = x0 + p0 * sigm4(g0), h1 = x1 + p1 * sigm4(g1);
;                         *(f32x4*)(H + off) = h0; *(f32x4*)(H + off + 4) = h1;
;                         ssv = ssv + h0 * h0; ssv = ssv + h1 * h1; }
;                     float ss = (ssv[0] + ssv[1]) + (ssv[2] + ssv[3]);
;                     ss += __shfl_xor(ss, 16); ss += __shfl_xor(ss, 32);
;                     if (fq == 0) unsafeAtomicAdd(rss3 + row, ss); }
	v_add_f32_e32 v194, v194, v195
	ds_bpermute_b32 v195, v59, v194
	s_waitcnt lgkmcnt(0)
	v_add_f32_e32 v194, v194, v195
	s_and_saveexec_b64 s[32:33], s[6:7]
	global_atomic_add_f32 v54, v194, s[70:71] offset:512
	s_or_b64 exec, exec, s[32:33]
	global_load_dword v66, v54, s[68:69] offset:640
	global_load_dwordx4 v[238:241], v56, s[86:87]
	global_load_dwordx4 v[242:245], v56, s[86:87] offset:256
	global_load_dwordx4 v[246:249], v56, s[88:89] nt
	global_load_dwordx4 v[250:253], v56, s[88:89] offset:256 nt
	s_add_u32 s86, s86, 0x20000
	s_addc_u32 s87, s87, 0
	s_add_u32 s88, s88, 0x20000
	s_addc_u32 s89, s89, 0
	s_waitcnt vmcnt(6)
	v_fmamk_f32 v186, v67, 0x39800000, v204
	v_mul_f32_e32 v187, 0x4f800000, v186
	v_cmp_gt_f32_e32 vcc, s67, v186
	s_nop 1
	v_cndmask_b32_e32 v186, v186, v187, vcc
	v_sqrt_f32_e32 v190, v186
	s_nop 0
	v_add_u32_e32 v191, -1, v190
	v_add_u32_e32 v192, 1, v190
	v_fma_f32 v193, -v191, v190, v186
	v_fma_f32 v187, -v192, v190, v186
	v_cmp_ge_f32_e64 s[10:11], 0, v193
	s_nop 1
	v_cndmask_b32_e64 v190, v190, v191, s[10:11]
	v_cmp_lt_f32_e64 s[10:11], 0, v187
	s_nop 1
	v_cndmask_b32_e64 v190, v190, v192, s[10:11]
	v_mul_f32_e32 v191, 0x37800000, v190
	v_cndmask_b32_e32 v190, v190, v191, vcc
	v_cmp_class_f32_e32 vcc, v186, v205
	s_nop 1
	v_cndmask_b32_e32 v186, v190, v186, vcc
	v_mul_f32_e32 v188, 0x3d112245, v186
	v_cvt_f32_i32_e32 v46, v46
	v_cvt_f32_i32_e32 v47, v47
	v_cvt_f32_i32_e32 v48, v48
	v_cvt_f32_i32_e32 v49, v49
	v_pk_mul_f32 v[142:143], v[222:223], v[188:189] op_sel_hi:[1,0]
	v_pk_mul_f32 v[144:145], v[224:225], v[188:189] op_sel_hi:[1,0]
	v_pk_fma_f32 v[154:155], v[142:143], v[46:47], v[206:207]
	v_pk_fma_f32 v[156:157], v[144:145], v[48:49], v[208:209]
	v_mul_f32_e32 v154, 0xbfb8aa3b, v154
	v_mul_f32_e32 v155, 0xbfb8aa3b, v155
	v_mul_f32_e32 v156, 0xbfb8aa3b, v156
	v_mul_f32_e32 v157, 0xbfb8aa3b, v157
	v_exp_f32_e32 v154, v154
	v_exp_f32_e32 v155, v155
	v_exp_f32_e32 v156, v156
	v_exp_f32_e32 v157, v157
	v_lshlrev_b32_e32 v146, 16, v170
	v_and_b32_e32 v147, 0xffff0000, v170
	v_lshlrev_b32_e32 v148, 16, v171
	v_and_b32_e32 v149, 0xffff0000, v171
	v_add_f32_e32 v154, 1.0, v154
	v_add_f32_e32 v155, 1.0, v155
	v_add_f32_e32 v156, 1.0, v156
	v_add_f32_e32 v157, 1.0, v157
	v_rcp_f32_e32 v154, v154
	v_rcp_f32_e32 v155, v155
	v_rcp_f32_e32 v156, v156
	v_rcp_f32_e32 v157, v157
	v_lshlrev_b32_e32 v150, 16, v178
	v_and_b32_e32 v151, 0xffff0000, v178
	v_lshlrev_b32_e32 v152, 16, v179
	v_and_b32_e32 v153, 0xffff0000, v179
	v_pk_fma_f32 v[46:47], v[154:155], v[150:151], v[146:147]
	v_pk_fma_f32 v[48:49], v[156:157], v[152:153], v[148:149]
	v_pk_mul_f32 v[194:195], v[46:47], v[46:47]
	v_pk_mul_f32 v[196:197], v[48:49], v[48:49]
	v_cvt_f32_i32_e32 v42, v42
	v_cvt_f32_i32_e32 v43, v43
	v_cvt_f32_i32_e32 v44, v44
	v_cvt_f32_i32_e32 v45, v45
	v_pk_mul_f32 v[142:143], v[226:227], v[188:189] op_sel_hi:[1,0]
	v_pk_mul_f32 v[144:145], v[228:229], v[188:189] op_sel_hi:[1,0]
	v_pk_fma_f32 v[154:155], v[142:143], v[42:43], v[210:211]
	v_pk_fma_f32 v[156:157], v[144:145], v[44:45], v[212:213]
	v_mul_f32_e32 v154, 0xbfb8aa3b, v154
	v_mul_f32_e32 v155, 0xbfb8aa3b, v155
	v_mul_f32_e32 v156, 0xbfb8aa3b, v156
	v_mul_f32_e32 v157, 0xbfb8aa3b, v157
	v_exp_f32_e32 v154, v154
	v_exp_f32_e32 v155, v155
	v_exp_f32_e32 v156, v156
	v_exp_f32_e32 v157, v157
	v_lshlrev_b32_e32 v146, 16, v172
	v_and_b32_e32 v147, 0xffff0000, v172
	v_lshlrev_b32_e32 v148, 16, v173
	v_and_b32_e32 v149, 0xffff0000, v173
	v_add_f32_e32 v154, 1.0, v154
	v_add_f32_e32 v155, 1.0, v155
	v_add_f32_e32 v156, 1.0, v156
	v_add_f32_e32 v157, 1.0, v157
	v_rcp_f32_e32 v154, v154
	v_rcp_f32_e32 v155, v155
	v_rcp_f32_e32 v156, v156
	v_rcp_f32_e32 v157, v157
	v_lshlrev_b32_e32 v150, 16, v180
	v_and_b32_e32 v151, 0xffff0000, v180
	v_lshlrev_b32_e32 v152, 16, v181
	v_and_b32_e32 v153, 0xffff0000, v181
	v_pk_fma_f32 v[42:43], v[154:155], v[150:151], v[146:147]
	v_pk_fma_f32 v[44:45], v[156:157], v[152:153], v[148:149]
	v_pk_fma_f32 v[194:195], v[42:43], v[42:43], v[194:195]
	v_pk_fma_f32 v[196:197], v[44:45], v[44:45], v[196:197]
	v_cvt_f32_i32_e32 v38, v38
	v_cvt_f32_i32_e32 v39, v39
	v_cvt_f32_i32_e32 v40, v40
	v_cvt_f32_i32_e32 v41, v41
	v_pk_mul_f32 v[142:143], v[230:231], v[188:189] op_sel_hi:[1,0]
	v_pk_mul_f32 v[144:145], v[232:233], v[188:189] op_sel_hi:[1,0]
	v_pk_fma_f32 v[154:155], v[142:143], v[38:39], v[214:215]
	v_pk_fma_f32 v[156:157], v[144:145], v[40:41], v[216:217]
	v_mul_f32_e32 v154, 0xbfb8aa3b, v154
	v_mul_f32_e32 v155, 0xbfb8aa3b, v155
	v_mul_f32_e32 v156, 0xbfb8aa3b, v156
	v_mul_f32_e32 v157, 0xbfb8aa3b, v157
	v_exp_f32_e32 v154, v154
	v_exp_f32_e32 v155, v155
	v_exp_f32_e32 v156, v156
	v_exp_f32_e32 v157, v157
	v_lshlrev_b32_e32 v146, 16, v174
	v_and_b32_e32 v147, 0xffff0000, v174
	v_lshlrev_b32_e32 v148, 16, v175
	v_and_b32_e32 v149, 0xffff0000, v175
	v_add_f32_e32 v154, 1.0, v154
	v_add_f32_e32 v155, 1.0, v155
	v_add_f32_e32 v156, 1.0, v156
	v_add_f32_e32 v157, 1.0, v157
	v_rcp_f32_e32 v154, v154
	v_rcp_f32_e32 v155, v155
	v_rcp_f32_e32 v156, v156
	v_rcp_f32_e32 v157, v157
	v_lshlrev_b32_e32 v150, 16, v182
	v_and_b32_e32 v151, 0xffff0000, v182
	v_lshlrev_b32_e32 v152, 16, v183
	v_and_b32_e32 v153, 0xffff0000, v183
	v_pk_fma_f32 v[38:39], v[154:155], v[150:151], v[146:147]
	v_pk_fma_f32 v[40:41], v[156:157], v[152:153], v[148:149]
	v_pk_fma_f32 v[194:195], v[38:39], v[38:39], v[194:195]
	v_pk_fma_f32 v[196:197], v[40:41], v[40:41], v[196:197]
	v_cvt_f32_i32_e32 v34, v34
	v_cvt_f32_i32_e32 v35, v35
	v_cvt_f32_i32_e32 v36, v36
	v_cvt_f32_i32_e32 v37, v37
	v_pk_mul_f32 v[142:143], v[234:235], v[188:189] op_sel_hi:[1,0]
	v_pk_mul_f32 v[144:145], v[236:237], v[188:189] op_sel_hi:[1,0]
	v_pk_fma_f32 v[154:155], v[142:143], v[34:35], v[218:219]
	v_pk_fma_f32 v[156:157], v[144:145], v[36:37], v[220:221]
	v_mul_f32_e32 v154, 0xbfb8aa3b, v154
	v_mul_f32_e32 v155, 0xbfb8aa3b, v155
	v_mul_f32_e32 v156, 0xbfb8aa3b, v156
	v_mul_f32_e32 v157, 0xbfb8aa3b, v157
	v_exp_f32_e32 v154, v154
	v_exp_f32_e32 v155, v155
	v_exp_f32_e32 v156, v156
	v_exp_f32_e32 v157, v157
	v_lshlrev_b32_e32 v146, 16, v176
	v_and_b32_e32 v147, 0xffff0000, v176
	v_lshlrev_b32_e32 v148, 16, v177
	v_and_b32_e32 v149, 0xffff0000, v177
	v_add_f32_e32 v154, 1.0, v154
	v_add_f32_e32 v155, 1.0, v155
	v_add_f32_e32 v156, 1.0, v156
	v_add_f32_e32 v157, 1.0, v157
	v_rcp_f32_e32 v154, v154
	v_rcp_f32_e32 v155, v155
	v_rcp_f32_e32 v156, v156
	v_rcp_f32_e32 v157, v157
	v_lshlrev_b32_e32 v150, 16, v184
	v_and_b32_e32 v151, 0xffff0000, v184
	v_lshlrev_b32_e32 v152, 16, v185
	v_and_b32_e32 v153, 0xffff0000, v185
	v_pk_fma_f32 v[34:35], v[154:155], v[150:151], v[146:147]
	v_pk_fma_f32 v[36:37], v[156:157], v[152:153], v[148:149]
	v_pk_fma_f32 v[194:195], v[34:35], v[34:35], v[194:195]
	v_pk_fma_f32 v[196:197], v[36:37], v[36:37], v[196:197]
	v_add_f32_e32 v194, v194, v195
	v_add_f32_e32 v196, v196, v197
	v_add_f32_e32 v194, v194, v196
	ds_bpermute_b32 v195, v58, v194
	s_waitcnt lgkmcnt(0)
; __device__ __forceinline__ f32x4 acc_i2f(const f32x4 a) { return __builtin_convertvector(__builtin_bit_cast(i32x4, a), f32x4); }
;     __device__ __forceinline__ void operator()(const f32x4 (&acc)[2][2][4][2], const pg8::Unit& u, int wr, int wc, int fr, int fq) const {
;     ...
;                 u32x4 hr[2][2], pr[2][2]; float q1v[2];
; #pragma unroll
;                 for (int mm = 0; mm < 2; ++mm) { const int row = row0 + ai * 128 + (2 * mp + mm) * 16; q1v[mm] = rss1[row];
; #pragma unroll
;                     for (int bj = 0; bj < 2; ++bj) { const size_t off = (size_t)row * DM + col0 + bj * 128; hr[mm][bj] = *(const u32x4*)(HB + off); pr[mm][bj] = *(const u32x4*)(PP + off); } }
; #pragma unroll
;                 for (int mm = 0; mm < 2; ++mm) { const int m = 2 * mp + mm, row = row0 + ai * 128 + m * 16; f32x4 ssv = {0.f, 0.f, 0.f, 0.f}; const float sa = (QCLIP / 127.f) * sqrtf(q1v[mm] * (1.f / DM) + EPS);
; #pragma unroll
;                     for (int bj = 0; bj < 2; ++bj) { const size_t off = (size_t)row * DM + col0 + bj * 128;
;                         f32x4 p0, p1, x0, x1; unpack8v(pr[mm][bj], p0, p1); unpack8v(hr[mm][bj], x0, x1);
;                         const f32x4 g0 = acc_i2f(acc[ai][bj][m][0]) * (sb[bj][0] * sa) + bv[bj][0], g1 = acc_i2f(acc[ai][bj][m][1]) * (sb[bj][1] * sa) + bv[bj][1];
;                         const f32x4 h0 = x0 + p0 * sigm4(g0), h1 = x1 + p1 * sigm4(g1);
;                         *(f32x4*)(H + off) = h0; *(f32x4*)(H + off + 4) = h1;
;                         ssv = ssv + h0 * h0; ssv = ssv + h1 * h1; }
;                     float ss = (ssv[0] + ssv[1]) + (ssv[2] + ssv[3]);
;                     ss += __shfl_xor(ss, 16); ss += __shfl_xor(ss, 32);
;                     if (fq == 0) unsafeAtomicAdd(rss3 + row, ss); }
	v_add_f32_e32 v194, v194, v195
	ds_bpermute_b32 v195, v59, v194
	s_waitcnt lgkmcnt(0)
	v_add_f32_e32 v194, v194, v195
	s_and_saveexec_b64 s[32:33], s[6:7]
	global_atomic_add_f32 v54, v194, s[70:71] offset:576
	s_or_b64 exec, exec, s[32:33]
	global_load_dword v67, v54, s[68:69] offset:704
	global_load_dwordx4 v[170:173], v56, s[86:87]
	global_load_dwordx4 v[174:177], v56, s[86:87] offset:256
	global_load_dwordx4 v[178:181], v56, s[88:89] nt
	global_load_dwordx4 v[182:185], v56, s[88:89] offset:256 nt
	s_waitcnt vmcnt(6)
	v_fmamk_f32 v186, v66, 0x39800000, v204
	v_mul_f32_e32 v187, 0x4f800000, v186
	v_cmp_gt_f32_e32 vcc, s67, v186
	s_nop 1
	v_cndmask_b32_e32 v186, v186, v187, vcc
	v_sqrt_f32_e32 v190, v186
	s_nop 0
	v_add_u32_e32 v191, -1, v190
	v_add_u32_e32 v192, 1, v190
	v_fma_f32 v193, -v191, v190, v186
	v_fma_f32 v187, -v192, v190, v186
	v_cmp_ge_f32_e64 s[10:11], 0, v193
	s_nop 1
	v_cndmask_b32_e64 v190, v190, v191, s[10:11]
	v_cmp_lt_f32_e64 s[10:11], 0, v187
	s_nop 1
	v_cndmask_b32_e64 v190, v190, v192, s[10:11]
	v_mul_f32_e32 v191, 0x37800000, v190
	v_cndmask_b32_e32 v190, v190, v191, vcc
	v_cmp_class_f32_e32 vcc, v186, v205
	s_nop 1
	v_cndmask_b32_e32 v186, v190, v186, vcc
	v_mul_f32_e32 v188, 0x3d112245, v186
	v_cvt_f32_i32_e32 v30, v30
	v_cvt_f32_i32_e32 v31, v31
	v_cvt_f32_i32_e32 v32, v32
	v_cvt_f32_i32_e32 v33, v33
	v_pk_mul_f32 v[142:143], v[222:223], v[188:189] op_sel_hi:[1,0]
	v_pk_mul_f32 v[144:145], v[224:225], v[188:189] op_sel_hi:[1,0]
	v_pk_fma_f32 v[154:155], v[142:143], v[30:31], v[206:207]
	v_pk_fma_f32 v[156:157], v[144:145], v[32:33], v[208:209]
	v_mul_f32_e32 v154, 0xbfb8aa3b, v154
	v_mul_f32_e32 v155, 0xbfb8aa3b, v155
	v_mul_f32_e32 v156, 0xbfb8aa3b, v156
	v_mul_f32_e32 v157, 0xbfb8aa3b, v157
	v_exp_f32_e32 v154, v154
	v_exp_f32_e32 v155, v155
	v_exp_f32_e32 v156, v156
	v_exp_f32_e32 v157, v157
	v_lshlrev_b32_e32 v146, 16, v238
	v_and_b32_e32 v147, 0xffff0000, v238
	v_lshlrev_b32_e32 v148, 16, v239
	v_and_b32_e32 v149, 0xffff0000, v239
	v_add_f32_e32 v154, 1.0, v154
	v_add_f32_e32 v155, 1.0, v155
	v_add_f32_e32 v156, 1.0, v156
	v_add_f32_e32 v157, 1.0, v157
	v_rcp_f32_e32 v154, v154
	v_rcp_f32_e32 v155, v155
	v_rcp_f32_e32 v156, v156
	v_rcp_f32_e32 v157, v157
	v_lshlrev_b32_e32 v150, 16, v246
	v_and_b32_e32 v151, 0xffff0000, v246
	v_lshlrev_b32_e32 v152, 16, v247
	v_and_b32_e32 v153, 0xffff0000, v247
	v_pk_fma_f32 v[30:31], v[154:155], v[150:151], v[146:147]
	v_pk_fma_f32 v[32:33], v[156:157], v[152:153], v[148:149]
	v_pk_mul_f32 v[194:195], v[30:31], v[30:31]
	v_pk_mul_f32 v[196:197], v[32:33], v[32:33]
	v_cvt_f32_i32_e32 v26, v26
	v_cvt_f32_i32_e32 v27, v27
	v_cvt_f32_i32_e32 v28, v28
	v_cvt_f32_i32_e32 v29, v29
	v_pk_mul_f32 v[142:143], v[226:227], v[188:189] op_sel_hi:[1,0]
	v_pk_mul_f32 v[144:145], v[228:229], v[188:189] op_sel_hi:[1,0]
	v_pk_fma_f32 v[154:155], v[142:143], v[26:27], v[210:211]
	v_pk_fma_f32 v[156:157], v[144:145], v[28:29], v[212:213]
	v_mul_f32_e32 v154, 0xbfb8aa3b, v154
	v_mul_f32_e32 v155, 0xbfb8aa3b, v155
	v_mul_f32_e32 v156, 0xbfb8aa3b, v156
	v_mul_f32_e32 v157, 0xbfb8aa3b, v157
	v_exp_f32_e32 v154, v154
	v_exp_f32_e32 v155, v155
	v_exp_f32_e32 v156, v156
	v_exp_f32_e32 v157, v157
	v_lshlrev_b32_e32 v146, 16, v240
	v_and_b32_e32 v147, 0xffff0000, v240
	v_lshlrev_b32_e32 v148, 16, v241
	v_and_b32_e32 v149, 0xffff0000, v241
	v_add_f32_e32 v154, 1.0, v154
	v_add_f32_e32 v155, 1.0, v155
	v_add_f32_e32 v156, 1.0, v156
	v_add_f32_e32 v157, 1.0, v157
	v_rcp_f32_e32 v154, v154
	v_rcp_f32_e32 v155, v155
	v_rcp_f32_e32 v156, v156
	v_rcp_f32_e32 v157, v157
	v_lshlrev_b32_e32 v150, 16, v248
	v_and_b32_e32 v151, 0xffff0000, v248
	v_lshlrev_b32_e32 v152, 16, v249
	v_and_b32_e32 v153, 0xffff0000, v249
	v_pk_fma_f32 v[26:27], v[154:155], v[150:151], v[146:147]
	v_pk_fma_f32 v[28:29], v[156:157], v[152:153], v[148:149]
	v_pk_fma_f32 v[194:195], v[26:27], v[26:27], v[194:195]
	v_pk_fma_f32 v[196:197], v[28:29], v[28:29], v[196:197]
	v_cvt_f32_i32_e32 v22, v22
	v_cvt_f32_i32_e32 v23, v23
	v_cvt_f32_i32_e32 v24, v24
	v_cvt_f32_i32_e32 v25, v25
	v_pk_mul_f32 v[142:143], v[230:231], v[188:189] op_sel_hi:[1,0]
	v_pk_mul_f32 v[144:145], v[232:233], v[188:189] op_sel_hi:[1,0]
	v_pk_fma_f32 v[154:155], v[142:143], v[22:23], v[214:215]
	v_pk_fma_f32 v[156:157], v[144:145], v[24:25], v[216:217]
	v_mul_f32_e32 v154, 0xbfb8aa3b, v154
	v_mul_f32_e32 v155, 0xbfb8aa3b, v155
	v_mul_f32_e32 v156, 0xbfb8aa3b, v156
	v_mul_f32_e32 v157, 0xbfb8aa3b, v157
	v_exp_f32_e32 v154, v154
	v_exp_f32_e32 v155, v155
	v_exp_f32_e32 v156, v156
	v_exp_f32_e32 v157, v157
	v_lshlrev_b32_e32 v146, 16, v242
	v_and_b32_e32 v147, 0xffff0000, v242
	v_lshlrev_b32_e32 v148, 16, v243
	v_and_b32_e32 v149, 0xffff0000, v243
	v_add_f32_e32 v154, 1.0, v154
	v_add_f32_e32 v155, 1.0, v155
	v_add_f32_e32 v156, 1.0, v156
	v_add_f32_e32 v157, 1.0, v157
	v_rcp_f32_e32 v154, v154
	v_rcp_f32_e32 v155, v155
	v_rcp_f32_e32 v156, v156
	v_rcp_f32_e32 v157, v157
	v_lshlrev_b32_e32 v150, 16, v250
	v_and_b32_e32 v151, 0xffff0000, v250
	v_lshlrev_b32_e32 v152, 16, v251
	v_and_b32_e32 v153, 0xffff0000, v251
	v_pk_fma_f32 v[22:23], v[154:155], v[150:151], v[146:147]
	v_pk_fma_f32 v[24:25], v[156:157], v[152:153], v[148:149]
	v_pk_fma_f32 v[194:195], v[22:23], v[22:23], v[194:195]
	v_pk_fma_f32 v[196:197], v[24:25], v[24:25], v[196:197]
	v_cvt_f32_i32_e32 v18, v18
	v_cvt_f32_i32_e32 v19, v19
	v_cvt_f32_i32_e32 v20, v20
	v_cvt_f32_i32_e32 v21, v21
	v_pk_mul_f32 v[142:143], v[234:235], v[188:189] op_sel_hi:[1,0]
	v_pk_mul_f32 v[144:145], v[236:237], v[188:189] op_sel_hi:[1,0]
	v_pk_fma_f32 v[154:155], v[142:143], v[18:19], v[218:219]
	v_pk_fma_f32 v[156:157], v[144:145], v[20:21], v[220:221]
	v_mul_f32_e32 v154, 0xbfb8aa3b, v154
	v_mul_f32_e32 v155, 0xbfb8aa3b, v155
	v_mul_f32_e32 v156, 0xbfb8aa3b, v156
	v_mul_f32_e32 v157, 0xbfb8aa3b, v157
	v_exp_f32_e32 v154, v154
	v_exp_f32_e32 v155, v155
	v_exp_f32_e32 v156, v156
	v_exp_f32_e32 v157, v157
	v_lshlrev_b32_e32 v146, 16, v244
	v_and_b32_e32 v147, 0xffff0000, v244
	v_lshlrev_b32_e32 v148, 16, v245
	v_and_b32_e32 v149, 0xffff0000, v245
	v_add_f32_e32 v154, 1.0, v154
	v_add_f32_e32 v155, 1.0, v155
	v_add_f32_e32 v156, 1.0, v156
	v_add_f32_e32 v157, 1.0, v157
	v_rcp_f32_e32 v154, v154
	v_rcp_f32_e32 v155, v155
	v_rcp_f32_e32 v156, v156
	v_rcp_f32_e32 v157, v157
	v_lshlrev_b32_e32 v150, 16, v252
	v_and_b32_e32 v151, 0xffff0000, v252
	v_lshlrev_b32_e32 v152, 16, v253
	v_and_b32_e32 v153, 0xffff0000, v253
	v_pk_fma_f32 v[18:19], v[154:155], v[150:151], v[146:147]
	v_pk_fma_f32 v[20:21], v[156:157], v[152:153], v[148:149]
	v_pk_fma_f32 v[194:195], v[18:19], v[18:19], v[194:195]
	v_pk_fma_f32 v[196:197], v[20:21], v[20:21], v[196:197]
	v_add_f32_e32 v194, v194, v195
	v_add_f32_e32 v196, v196, v197
	v_add_f32_e32 v194, v194, v196
	ds_bpermute_b32 v195, v58, v194
	s_waitcnt lgkmcnt(0)
; __device__ __forceinline__ f32x4 acc_i2f(const f32x4 a) { return __builtin_convertvector(__builtin_bit_cast(i32x4, a), f32x4); }
;     __device__ __forceinline__ void operator()(const f32x4 (&acc)[2][2][4][2], const pg8::Unit& u, int wr, int wc, int fr, int fq) const {
;     ...
;                 for (int mm = 0; mm < 2; ++mm) { const int m = 2 * mp + mm, row = row0 + ai * 128 + m * 16; f32x4 ssv = {0.f, 0.f, 0.f, 0.f}; const float sa = (QCLIP / 127.f) * sqrtf(q1v[mm] * (1.f / DM) + EPS);
; #pragma unroll
;                     for (int bj = 0; bj < 2; ++bj) { const size_t off = (size_t)row * DM + col0 + bj * 128;
;                         f32x4 p0, p1, x0, x1; unpack8v(pr[mm][bj], p0, p1); unpack8v(hr[mm][bj], x0, x1);
;                         const f32x4 g0 = acc_i2f(acc[ai][bj][m][0]) * (sb[bj][0] * sa) + bv[bj][0], g1 = acc_i2f(acc[ai][bj][m][1]) * (sb[bj][1] * sa) + bv[bj][1];
;                         const f32x4 h0 = x0 + p0 * sigm4(g0), h1 = x1 + p1 * sigm4(g1);
;                         *(f32x4*)(H + off) = h0; *(f32x4*)(H + off + 4) = h1;
;                         ssv = ssv + h0 * h0; ssv = ssv + h1 * h1; }
;                     float ss = (ssv[0] + ssv[1]) + (ssv[2] + ssv[3]);
;                     ss += __shfl_xor(ss, 16); ss += __shfl_xor(ss, 32);
;                     if (fq == 0) unsafeAtomicAdd(rss3 + row, ss); }
;                 asm volatile("" ::: "memory"); }
	v_add_f32_e32 v194, v194, v195
	ds_bpermute_b32 v195, v59, v194
	s_waitcnt lgkmcnt(0)
	v_add_f32_e32 v194, v194, v195
	s_and_saveexec_b64 s[32:33], s[6:7]
	global_atomic_add_f32 v54, v194, s[70:71] offset:640
	s_or_b64 exec, exec, s[32:33]
	s_waitcnt vmcnt(1)
	v_fmamk_f32 v186, v67, 0x39800000, v204
	v_mul_f32_e32 v187, 0x4f800000, v186
	v_cmp_gt_f32_e32 vcc, s67, v186
	s_nop 1
	v_cndmask_b32_e32 v186, v186, v187, vcc
	v_sqrt_f32_e32 v190, v186
	s_nop 0
	v_add_u32_e32 v191, -1, v190
	v_add_u32_e32 v192, 1, v190
	v_fma_f32 v193, -v191, v190, v186
	v_fma_f32 v187, -v192, v190, v186
	v_cmp_ge_f32_e64 s[10:11], 0, v193
	s_nop 1
	v_cndmask_b32_e64 v190, v190, v191, s[10:11]
	v_cmp_lt_f32_e64 s[10:11], 0, v187
	s_nop 1
	v_cndmask_b32_e64 v190, v190, v192, s[10:11]
	v_mul_f32_e32 v191, 0x37800000, v190
	v_cndmask_b32_e32 v190, v190, v191, vcc
	v_cmp_class_f32_e32 vcc, v186, v205
	s_nop 1
	v_cndmask_b32_e32 v186, v190, v186, vcc
	v_mul_f32_e32 v188, 0x3d112245, v186
	v_cvt_f32_i32_e32 v14, v14
	v_cvt_f32_i32_e32 v15, v15
	v_cvt_f32_i32_e32 v16, v16
	v_cvt_f32_i32_e32 v17, v17
	v_pk_mul_f32 v[142:143], v[222:223], v[188:189] op_sel_hi:[1,0]
	v_pk_mul_f32 v[144:145], v[224:225], v[188:189] op_sel_hi:[1,0]
	v_pk_fma_f32 v[154:155], v[142:143], v[14:15], v[206:207]
	v_pk_fma_f32 v[156:157], v[144:145], v[16:17], v[208:209]
	v_mul_f32_e32 v154, 0xbfb8aa3b, v154
	v_mul_f32_e32 v155, 0xbfb8aa3b, v155
	v_mul_f32_e32 v156, 0xbfb8aa3b, v156
	v_mul_f32_e32 v157, 0xbfb8aa3b, v157
	v_exp_f32_e32 v154, v154
	v_exp_f32_e32 v155, v155
	v_exp_f32_e32 v156, v156
	v_exp_f32_e32 v157, v157
	v_lshlrev_b32_e32 v146, 16, v170
	v_and_b32_e32 v147, 0xffff0000, v170
	v_lshlrev_b32_e32 v148, 16, v171
	v_and_b32_e32 v149, 0xffff0000, v171
	v_add_f32_e32 v154, 1.0, v154
	v_add_f32_e32 v155, 1.0, v155
	v_add_f32_e32 v156, 1.0, v156
	v_add_f32_e32 v157, 1.0, v157
	v_rcp_f32_e32 v154, v154
	v_rcp_f32_e32 v155, v155
	v_rcp_f32_e32 v156, v156
	v_rcp_f32_e32 v157, v157
	v_lshlrev_b32_e32 v150, 16, v178
	v_and_b32_e32 v151, 0xffff0000, v178
	v_lshlrev_b32_e32 v152, 16, v179
	v_and_b32_e32 v153, 0xffff0000, v179
	v_pk_fma_f32 v[14:15], v[154:155], v[150:151], v[146:147]
	v_pk_fma_f32 v[16:17], v[156:157], v[152:153], v[148:149]
	v_pk_mul_f32 v[194:195], v[14:15], v[14:15]
	v_pk_mul_f32 v[196:197], v[16:17], v[16:17]
	v_cvt_f32_i32_e32 v10, v10
	v_cvt_f32_i32_e32 v11, v11
	v_cvt_f32_i32_e32 v12, v12
	v_cvt_f32_i32_e32 v13, v13
	v_pk_mul_f32 v[142:143], v[226:227], v[188:189] op_sel_hi:[1,0]
	v_pk_mul_f32 v[144:145], v[228:229], v[188:189] op_sel_hi:[1,0]
	v_pk_fma_f32 v[154:155], v[142:143], v[10:11], v[210:211]
	v_pk_fma_f32 v[156:157], v[144:145], v[12:13], v[212:213]
	v_mul_f32_e32 v154, 0xbfb8aa3b, v154
	v_mul_f32_e32 v155, 0xbfb8aa3b, v155
	v_mul_f32_e32 v156, 0xbfb8aa3b, v156
	v_mul_f32_e32 v157, 0xbfb8aa3b, v157
	v_exp_f32_e32 v154, v154
	v_exp_f32_e32 v155, v155
	v_exp_f32_e32 v156, v156
	v_exp_f32_e32 v157, v157
	v_lshlrev_b32_e32 v146, 16, v172
	v_and_b32_e32 v147, 0xffff0000, v172
	v_lshlrev_b32_e32 v148, 16, v173
	v_and_b32_e32 v149, 0xffff0000, v173
	v_add_f32_e32 v154, 1.0, v154
	v_add_f32_e32 v155, 1.0, v155
	v_add_f32_e32 v156, 1.0, v156
	v_add_f32_e32 v157, 1.0, v157
	v_rcp_f32_e32 v154, v154
	v_rcp_f32_e32 v155, v155
	v_rcp_f32_e32 v156, v156
	v_rcp_f32_e32 v157, v157
	v_lshlrev_b32_e32 v150, 16, v180
	v_and_b32_e32 v151, 0xffff0000, v180
	v_lshlrev_b32_e32 v152, 16, v181
	v_and_b32_e32 v153, 0xffff0000, v181
	v_pk_fma_f32 v[10:11], v[154:155], v[150:151], v[146:147]
	v_pk_fma_f32 v[12:13], v[156:157], v[152:153], v[148:149]
	v_pk_fma_f32 v[194:195], v[10:11], v[10:11], v[194:195]
	v_pk_fma_f32 v[196:197], v[12:13], v[12:13], v[196:197]
	v_cvt_f32_i32_e32 v6, v6
	v_cvt_f32_i32_e32 v7, v7
	v_cvt_f32_i32_e32 v8, v8
	v_cvt_f32_i32_e32 v9, v9
	v_pk_mul_f32 v[142:143], v[230:231], v[188:189] op_sel_hi:[1,0]
	v_pk_mul_f32 v[144:145], v[232:233], v[188:189] op_sel_hi:[1,0]
	v_pk_fma_f32 v[154:155], v[142:143], v[6:7], v[214:215]
	v_pk_fma_f32 v[156:157], v[144:145], v[8:9], v[216:217]
	v_mul_f32_e32 v154, 0xbfb8aa3b, v154
	v_mul_f32_e32 v155, 0xbfb8aa3b, v155
	v_mul_f32_e32 v156, 0xbfb8aa3b, v156
	v_mul_f32_e32 v157, 0xbfb8aa3b, v157
	v_exp_f32_e32 v154, v154
	v_exp_f32_e32 v155, v155
	v_exp_f32_e32 v156, v156
	v_exp_f32_e32 v157, v157
	v_lshlrev_b32_e32 v146, 16, v174
	v_and_b32_e32 v147, 0xffff0000, v174
	v_lshlrev_b32_e32 v148, 16, v175
	v_and_b32_e32 v149, 0xffff0000, v175
	v_add_f32_e32 v154, 1.0, v154
	v_add_f32_e32 v155, 1.0, v155
	v_add_f32_e32 v156, 1.0, v156
	v_add_f32_e32 v157, 1.0, v157
	v_rcp_f32_e32 v154, v154
	v_rcp_f32_e32 v155, v155
	v_rcp_f32_e32 v156, v156
	v_rcp_f32_e32 v157, v157
	v_lshlrev_b32_e32 v150, 16, v182
	v_and_b32_e32 v151, 0xffff0000, v182
	v_lshlrev_b32_e32 v152, 16, v183
	v_and_b32_e32 v153, 0xffff0000, v183
	v_pk_fma_f32 v[6:7], v[154:155], v[150:151], v[146:147]
	v_pk_fma_f32 v[8:9], v[156:157], v[152:153], v[148:149]
	v_pk_fma_f32 v[194:195], v[6:7], v[6:7], v[194:195]
	v_pk_fma_f32 v[196:197], v[8:9], v[8:9], v[196:197]
	v_cvt_f32_i32_e32 v2, v2
	v_cvt_f32_i32_e32 v3, v3
	v_cvt_f32_i32_e32 v4, v4
	v_cvt_f32_i32_e32 v5, v5
	v_pk_mul_f32 v[142:143], v[234:235], v[188:189] op_sel_hi:[1,0]
	v_pk_mul_f32 v[144:145], v[236:237], v[188:189] op_sel_hi:[1,0]
	v_pk_fma_f32 v[154:155], v[142:143], v[2:3], v[218:219]
	v_pk_fma_f32 v[156:157], v[144:145], v[4:5], v[220:221]
	v_mul_f32_e32 v154, 0xbfb8aa3b, v154
	v_mul_f32_e32 v155, 0xbfb8aa3b, v155
	v_mul_f32_e32 v156, 0xbfb8aa3b, v156
	v_mul_f32_e32 v157, 0xbfb8aa3b, v157
	v_exp_f32_e32 v154, v154
	v_exp_f32_e32 v155, v155
	v_exp_f32_e32 v156, v156
	v_exp_f32_e32 v157, v157
	v_lshlrev_b32_e32 v146, 16, v176
	v_and_b32_e32 v147, 0xffff0000, v176
	v_lshlrev_b32_e32 v148, 16, v177
	v_and_b32_e32 v149, 0xffff0000, v177
	v_add_f32_e32 v154, 1.0, v154
	v_add_f32_e32 v155, 1.0, v155
	v_add_f32_e32 v156, 1.0, v156
	v_add_f32_e32 v157, 1.0, v157
	v_rcp_f32_e32 v154, v154
	v_rcp_f32_e32 v155, v155
	v_rcp_f32_e32 v156, v156
	v_rcp_f32_e32 v157, v157
	v_lshlrev_b32_e32 v150, 16, v184
	v_and_b32_e32 v151, 0xffff0000, v184
	v_lshlrev_b32_e32 v152, 16, v185
	v_and_b32_e32 v153, 0xffff0000, v185
	v_pk_fma_f32 v[2:3], v[154:155], v[150:151], v[146:147]
	v_pk_fma_f32 v[4:5], v[156:157], v[152:153], v[148:149]
	v_pk_fma_f32 v[194:195], v[2:3], v[2:3], v[194:195]
	v_pk_fma_f32 v[196:197], v[4:5], v[4:5], v[196:197]
	v_add_f32_e32 v194, v194, v195
	v_add_f32_e32 v196, v196, v197
	v_add_f32_e32 v194, v194, v196
	ds_bpermute_b32 v195, v58, v194
	s_waitcnt lgkmcnt(0)
	v_add_f32_e32 v194, v194, v195
	ds_bpermute_b32 v195, v59, v194
	s_waitcnt lgkmcnt(0)
	v_add_f32_e32 v194, v194, v195
	s_and_saveexec_b64 s[32:33], s[6:7]
	global_atomic_add_f32 v54, v194, s[70:71] offset:704
	s_or_b64 exec, exec, s[32:33]
	s_waitcnt vmcnt(0)
	s_barrier
; #define SEAM(k) do { if (IN(k) && IN((k) + 1)) xcd_barrier(bar); } while (0)
; __global__ void __launch_bounds__(512, 2) k_fwd(Args a_unused) {
;     ...
;     if (IN(8)) { PH_IDS();
;         pg8::Gemm g{(const bf16_t*)(ws + WS_H2Q), (const bf16_t*)(ws + WS_WG), SEQ, DM, DM}; pg8::StaticOrder S; S.init(SEQ, DM, G, c);
;         EpiGate E{0, ap->out, (const bf16_t*)(ws + WS_XB), (const bf16_t*)(ws + WS_PP), ap->in[19], ctl + CW_RSS3, ctl + CW_RSS1, ctl + CW_CMAX_G};
;         pg8::gemm_phase<EpiGate, pg8::StaticOrder, true, true>(lds, g, S, E);
;     }
;     SEAM(8);
;     if (IN(9)) { PH_IDS(); ph_final_norm(ap->out, ctl + CW_RSS3, ap->in[21], gt, NGT); }
	s_load_dwordx2 s[100:101], s[92:93], 0xa8
	s_lshl_b32 s48, s98, 7
	s_add_u32 s50, s26, s48
	s_addc_u32 s51, s27, 0
	s_add_u32 s50, s50, 0x10000
	s_addc_u32 s51, s51, 0
	s_and_saveexec_b64 s[52:53], s[96:97]
	s_cbranch_execz .Lfz_poll_done
	v_mov_b32_e32 v60, 0
	v_mov_b32_e32 v61, 1
	global_atomic_add v60, v61, s[50:51]
	s_mov_b32 s49, 0
